# K2 + rmsnorm rstd via v_rsq_f32 (f32; the reference uses lax.rsqrt) instead of the IEEE sqrt+divide expansion at 13 sites in split/post phases
# speedup vs baseline: 1.0617x; 1.0022x over previous
.LBB0_182:
	v_lshlrev_b32_e32 v84, 16, v78
	v_and_b32_e32 v85, 0xffff0000, v78
	v_lshlrev_b32_e32 v86, 16, v79
	s_waitcnt lgkmcnt(0)
	v_and_b32_e32 v87, 0xffff0000, v79
	v_lshlrev_b32_e32 v20, 16, v74
	v_and_b32_e32 v21, 0xffff0000, v74
	v_lshlrev_b32_e32 v22, 16, v75
	v_and_b32_e32 v23, 0xffff0000, v75
	v_lshlrev_b32_e32 v74, 16, v72
	v_and_b32_e32 v75, 0xffff0000, v72
	v_lshlrev_b32_e32 v78, 16, v70
	v_and_b32_e32 v79, 0xffff0000, v70
	s_lshl_b64 s[6:7], s[4:5], 7
	v_lshlrev_b32_e32 v82, 16, v71
	v_and_b32_e32 v83, 0xffff0000, v71
	v_pk_mul_f32 v[70:71], v[74:75], v[78:79]
	v_lshl_add_u64 v[74:75], v[44:45], 0, s[6:7]
	v_cvt_pk_bf16_f32 v78, v80, v81
	global_store_short v[74:75], v78, off
	v_mul_f32_e32 v74, 0x3d372713, v84
	v_mul_f32_e32 v74, v74, v84
	v_fma_f32 v74, v74, v84, v84
	v_mul_f32_e32 v74, 0x3f4c422a, v74
	v_mul_f32_e32 v74, -2.0, v74
	v_mul_f32_e32 v74, 0x3fb8aa3b, v74
	v_exp_f32_e32 v74, v74
	v_lshlrev_b32_e32 v72, 16, v73
	v_and_b32_e32 v73, 0xffff0000, v73
	v_pk_mul_f32 v[72:73], v[72:73], v[82:83]
	v_add_f32_e32 v74, 1.0, v74
	v_div_scale_f32 v75, s[6:7], v74, v74, v84
	v_rcp_f32_e32 v78, v75
	v_lshlrev_b32_e32 v88, 16, v76
	v_and_b32_e32 v89, 0xffff0000, v76
	v_lshlrev_b32_e32 v76, 16, v77
	v_fma_f32 v79, -v75, v78, 1.0
	v_fmac_f32_e32 v78, v79, v78
	v_div_scale_f32 v79, vcc, v84, v74, v84
	v_mul_f32_e32 v80, v79, v78
	v_fma_f32 v82, -v75, v80, v79
	v_fmac_f32_e32 v80, v82, v78
	v_fma_f32 v75, -v75, v80, v79
	v_div_fmas_f32 v75, v75, v78, v80
	v_div_fixup_f32 v74, v75, v74, v84
	v_mul_f32_e32 v75, 0x3d372713, v85
	v_mul_f32_e32 v75, v75, v85
	v_fma_f32 v75, v75, v85, v85
	v_mul_f32_e32 v75, 0x3f4c422a, v75
	v_mul_f32_e32 v75, -2.0, v75
	v_mul_f32_e32 v75, 0x3fb8aa3b, v75
	v_exp_f32_e32 v75, v75
	v_and_b32_e32 v77, 0xffff0000, v77
	v_pk_mul_f32 v[64:65], v[10:11], v[64:65]
	v_pk_mul_f32 v[66:67], v[8:9], v[66:67]
	v_add_f32_e32 v75, 1.0, v75
	v_div_scale_f32 v78, s[6:7], v75, v75, v85
	v_rcp_f32_e32 v79, v78
	v_pk_fma_f32 v[64:65], v[14:15], v[72:73], v[64:65]
	v_pk_fma_f32 v[66:67], v[12:13], v[70:71], v[66:67]
	v_pk_fma_f32 v[64:65], v[18:19], v[68:69], v[64:65]
	v_fma_f32 v80, -v78, v79, 1.0
	v_fmac_f32_e32 v79, v80, v79
	v_div_scale_f32 v80, vcc, v85, v75, v85
	v_mul_f32_e32 v82, v80, v79
	v_fma_f32 v83, -v78, v82, v80
	v_fmac_f32_e32 v82, v83, v79
	v_fma_f32 v78, -v78, v82, v80
	v_div_fmas_f32 v78, v78, v79, v82
	v_div_fixup_f32 v75, v78, v75, v85
	v_mul_f32_e32 v78, 0x3d372713, v86
	v_mul_f32_e32 v78, v78, v86
	v_fma_f32 v78, v78, v86, v86
	v_mul_f32_e32 v78, 0x3f4c422a, v78
	v_mul_f32_e32 v78, -2.0, v78
	v_mul_f32_e32 v78, 0x3fb8aa3b, v78
	v_exp_f32_e32 v78, v78
	v_cvt_pk_bf16_f32 v74, v74, v75
	v_pk_fma_f32 v[62:63], v[16:17], v[62:63], v[66:67]
	v_pk_mul_f32 v[22:23], v[64:65], v[22:23]
	v_add_f32_e32 v78, 1.0, v78
	v_div_scale_f32 v79, s[6:7], v78, v78, v86
	v_rcp_f32_e32 v80, v79
	v_pk_mul_f32 v[20:21], v[62:63], v[20:21]
	v_lshl_add_u64 v[48:49], v[48:49], 0, s[16:17]
	v_lshl_add_u64 v[50:51], v[50:51], 0, s[30:31]
	v_fma_f32 v82, -v79, v80, 1.0
	v_fmac_f32_e32 v80, v82, v80
	v_div_scale_f32 v82, vcc, v86, v78, v86
	v_mul_f32_e32 v83, v82, v80
	v_fma_f32 v84, -v79, v83, v82
	v_fmac_f32_e32 v83, v84, v80
	v_fma_f32 v79, -v79, v83, v82
	v_div_fmas_f32 v79, v79, v80, v83
	v_div_fixup_f32 v78, v79, v78, v86
	v_mul_f32_e32 v79, 0x3d372713, v87
	v_mul_f32_e32 v79, v79, v87
	v_fma_f32 v79, v79, v87, v87
	v_mul_f32_e32 v79, 0x3f4c422a, v79
	v_mul_f32_e32 v79, -2.0, v79
	v_mul_f32_e32 v79, 0x3fb8aa3b, v79
	v_exp_f32_e32 v79, v79
	v_lshl_add_u64 v[52:53], v[52:53], 0, s[98:99]
	v_lshl_add_u64 v[54:55], v[54:55], 0, s[14:15]
	v_lshl_add_u64 v[56:57], v[56:57], 0, s[34:35]
	v_add_f32_e32 v79, 1.0, v79
	v_div_scale_f32 v80, s[6:7], v79, v79, v87
	v_rcp_f32_e32 v82, v80
	s_lshl_b64 s[6:7], s[0:1], 1
	v_lshl_add_u64 v[58:59], v[58:59], 0, s[34:35]
	v_lshl_add_u64 v[60:61], v[60:61], 0, s[34:35]
	v_fma_f32 v83, -v80, v82, 1.0
	v_fmac_f32_e32 v82, v83, v82
	v_div_scale_f32 v83, vcc, v87, v79, v87
	v_mul_f32_e32 v84, v83, v82
	v_fma_f32 v85, -v80, v84, v83
	v_fmac_f32_e32 v84, v85, v82
	v_fma_f32 v80, -v80, v84, v83
	v_div_fmas_f32 v80, v80, v82, v84
	v_div_fixup_f32 v79, v80, v79, v87
	v_cvt_pk_bf16_f32 v75, v78, v79
	v_lshl_add_u64 v[78:79], v[40:41], 0, s[6:7]
	global_store_dwordx2 v[78:79], v[74:75], off
	v_mul_f32_e32 v74, 0x3d372713, v88
	v_mul_f32_e32 v75, 0x3d372713, v89
	v_mul_f32_e32 v74, v74, v88
	v_mul_f32_e32 v75, v75, v89
	v_fma_f32 v74, v74, v88, v88
	v_fma_f32 v75, v75, v89, v89
	v_mul_f32_e32 v74, 0x3f4c422a, v74
	v_mul_f32_e32 v75, 0x3f4c422a, v75
	v_mul_f32_e32 v74, -2.0, v74
	v_mul_f32_e32 v75, -2.0, v75
	v_mul_f32_e32 v74, 0x3fb8aa3b, v74
	v_mul_f32_e32 v75, 0x3fb8aa3b, v75
	v_exp_f32_e32 v74, v74
	v_exp_f32_e32 v75, v75
	s_nop 0
	v_pk_add_f32 v[74:75], v[74:75], 1.0 op_sel_hi:[1,0]
	s_nop 0
	v_div_scale_f32 v78, s[0:1], v75, v75, v89
	v_rcp_f32_e32 v79, v78
	s_nop 0
	v_fma_f32 v80, -v78, v79, 1.0
	v_fmac_f32_e32 v79, v80, v79
	v_div_scale_f32 v80, vcc, v89, v75, v89
	v_mul_f32_e32 v82, v80, v79
	v_fma_f32 v83, -v78, v82, v80
	v_fmac_f32_e32 v82, v83, v79
	v_fma_f32 v78, -v78, v82, v80
	v_div_fmas_f32 v78, v78, v79, v82
	v_div_fixup_f32 v75, v78, v75, v89
	v_div_scale_f32 v78, s[0:1], v74, v74, v88
	v_rcp_f32_e32 v79, v78
	s_nop 0
	v_fma_f32 v80, -v78, v79, 1.0
	v_fmac_f32_e32 v79, v80, v79
	v_div_scale_f32 v80, vcc, v88, v74, v88
	v_mul_f32_e32 v82, v80, v79
	v_fma_f32 v83, -v78, v82, v80
	v_fmac_f32_e32 v82, v83, v79
	v_fma_f32 v78, -v78, v82, v80
	v_div_fmas_f32 v78, v78, v79, v82
	v_div_fixup_f32 v74, v78, v74, v88
	v_mul_f32_e32 v78, 0x3d372713, v76
	v_mul_f32_e32 v79, 0x3d372713, v77
	v_mul_f32_e32 v78, v78, v76
	v_mul_f32_e32 v79, v79, v77
	v_fma_f32 v78, v78, v76, v76
	v_fma_f32 v79, v79, v77, v77
	v_mul_f32_e32 v78, 0x3f4c422a, v78
	v_mul_f32_e32 v79, 0x3f4c422a, v79
	v_mul_f32_e32 v78, -2.0, v78
	v_mul_f32_e32 v79, -2.0, v79
	v_mul_f32_e32 v78, 0x3fb8aa3b, v78
	v_mul_f32_e32 v79, 0x3fb8aa3b, v79
	v_exp_f32_e32 v78, v78
	v_exp_f32_e32 v79, v79
	s_nop 0
	v_pk_add_f32 v[78:79], v[78:79], 1.0 op_sel_hi:[1,0]
	s_nop 0
	v_div_scale_f32 v80, s[0:1], v79, v79, v77
	v_rcp_f32_e32 v82, v80
	s_nop 0
	v_fma_f32 v83, -v80, v82, 1.0
	v_fmac_f32_e32 v82, v83, v82
	v_div_scale_f32 v83, vcc, v77, v79, v77
	v_mul_f32_e32 v84, v83, v82
	v_fma_f32 v85, -v80, v84, v83
	v_fmac_f32_e32 v84, v85, v82
	v_fma_f32 v80, -v80, v84, v83
	v_div_fmas_f32 v80, v80, v82, v84
	v_div_fixup_f32 v77, v80, v79, v77
	v_div_scale_f32 v79, s[0:1], v78, v78, v76
	v_rcp_f32_e32 v80, v79
	s_nop 0
	v_fma_f32 v82, -v79, v80, 1.0
	v_fmac_f32_e32 v80, v82, v80
	v_div_scale_f32 v82, vcc, v76, v78, v76
	v_mul_f32_e32 v83, v82, v80
	v_fma_f32 v84, -v79, v83, v82
	v_fmac_f32_e32 v83, v84, v80
	v_fma_f32 v79, -v79, v83, v82
	v_div_fmas_f32 v79, v79, v80, v83
	v_div_fixup_f32 v76, v79, v78, v76
	v_mov_b32_e32 v82, v75
	v_mov_b32_e32 v83, v77
	v_mov_b32_e32 v78, v74
	v_mov_b32_e32 v79, v76
	v_pk_mul_f32 v[82:83], v[82:83], v[82:83]
	s_nop 0
	v_pk_fma_f32 v[78:79], v[78:79], v[78:79], v[82:83]
	s_nop 0
	v_add_f32_e32 v78, v78, v79
	s_nop 1
	v_add_f32_dpp v78, v78, v78 quad_perm:[1,0,3,2] row_mask:0xf bank_mask:0xf bound_ctrl:1
	s_nop 1
	v_add_f32_dpp v78, v78, v78 quad_perm:[2,3,0,1] row_mask:0xf bank_mask:0xf bound_ctrl:1
	s_nop 1
	v_add_f32_dpp v78, v78, v78 row_half_mirror row_mask:0xf bank_mask:0xf bound_ctrl:1
	s_nop 1
	v_add_f32_dpp v78, v78, v78 row_mirror row_mask:0xf bank_mask:0xf bound_ctrl:1
	s_nop 0
	v_readlane_b32 s18, v78, 16
	v_readlane_b32 s26, v78, 48
	v_readlane_b32 s0, v78, 0
	v_readlane_b32 s1, v78, 32
	v_mov_b32_e32 v78, s18
	v_mov_b32_e32 v79, s26
	v_pk_add_f32 v[78:79], s[0:1], v[78:79]
	s_nop 0
	v_add_f32_e32 v78, v78, v79
	v_fmamk_f32 v78, v78, 0x3b800000, v218
	s_nop 0
	s_nop 0
	s_nop 0
	s_nop 1
	s_nop 1
	s_lshl_b64 s[0:1], s[4:5], 11
	s_add_u32 s0, s42, s0
	s_addc_u32 s1, s43, s1
	v_rsq_f32_e32 v78, v78
	s_nop 0
	v_pk_mul_f32 v[74:75], v[74:75], v[78:79] op_sel_hi:[1,0]
	v_pk_mul_f32 v[76:77], v[76:77], v[78:79] op_sel_hi:[1,0]
	v_pk_mul_f32 v[74:75], v[4:5], v[74:75]
	v_pk_mul_f32 v[76:77], v[6:7], v[76:77]
	v_cvt_pk_bf16_f32 v74, v74, v75
	s_add_i32 s11, s11, s10
	v_cvt_pk_bf16_f32 v75, v76, v77
	v_lshl_add_u64 v[76:77], v[42:43], 0, s[6:7]
	global_store_dwordx2 v[76:77], v[74:75], off
	v_cvt_pk_bf16_f32 v20, v20, v21
	v_cvt_pk_bf16_f32 v21, v22, v23
	v_lshl_add_u64 v[22:23], v[26:27], 1, s[0:1]
	v_add_co_u32_e32 v22, vcc, s65, v22
	s_cmpk_gt_i32 s11, 0x2fff
	s_nop 0
	v_addc_co_u32_e32 v23, vcc, 0, v23, vcc
	global_store_dwordx2 v[22:23], v[20:21], off offset:1536
	s_cbranch_scc1 .LBB0_216

.LBB0_195:
	s_waitcnt vmcnt(0)
	v_and_b32_e32 v116, 0xffff0000, v109
	v_and_b32_e32 v118, 0xffff0000, v108
	v_lshlrev_b32_e32 v113, 16, v109
	v_lshlrev_b32_e32 v117, 16, v108
	v_mul_f32_e32 v22, v116, v116
	v_mul_f32_e32 v23, v118, v118
	v_lshlrev_b32_e32 v119, 16, v95
	v_and_b32_e32 v95, 0xffff0000, v95
	v_fmac_f32_e32 v22, v113, v113
	v_fmac_f32_e32 v23, v117, v117
	v_add_f32_e32 v22, v22, v23
	v_mul_f32_e32 v23, v95, v95
	v_fmac_f32_e32 v23, v119, v119
	v_add_f32_e32 v22, v22, v23
	s_nop 1
	v_add_f32_dpp v22, v22, v22 quad_perm:[1,0,3,2] row_mask:0xf bank_mask:0xf bound_ctrl:1
	s_nop 1
	v_add_f32_dpp v22, v22, v22 quad_perm:[2,3,0,1] row_mask:0xf bank_mask:0xf bound_ctrl:1
	s_nop 1
	v_add_f32_dpp v22, v22, v22 row_half_mirror row_mask:0xf bank_mask:0xf bound_ctrl:1
	s_nop 1
	v_add_f32_dpp v22, v22, v22 row_mirror row_mask:0xf bank_mask:0xf bound_ctrl:1
	s_nop 0
	v_readlane_b32 s1, v22, 16
	v_readlane_b32 s0, v22, 0
	s_nop 0
	v_mov_b32_e32 v23, s1
	v_readlane_b32 s1, v22, 48
	v_add_f32_e32 v23, s0, v23
	v_readlane_b32 s0, v22, 32
	v_mov_b32_e32 v22, s1
	s_nop 0
	v_add_f32_e32 v22, s0, v22
	v_add_f32_e32 v22, v23, v22
	v_fmamk_f32 v22, v22, 0x3b2aaaab, v218
	v_mul_f32_e32 v23, 0x4f800000, v22
	v_cmp_gt_f32_e32 vcc, s25, v22
	s_nop 1
	v_cndmask_b32_e32 v22, v22, v23, vcc
	v_sqrt_f32_e32 v108, v22
	v_lshlrev_b32_e32 v23, 16, v21
	v_and_b32_e32 v21, 0xffff0000, v21
	v_add_u32_e32 v109, -1, v108
	v_fma_f32 v120, -v109, v108, v22
	v_cmp_ge_f32_e64 s[0:1], 0, v120
	v_add_u32_e32 v120, 1, v108
	s_nop 0
	v_cndmask_b32_e64 v109, v108, v109, s[0:1]
	v_fma_f32 v108, -v120, v108, v22
	v_cmp_lt_f32_e64 s[0:1], 0, v108
	s_nop 1
	v_cndmask_b32_e64 v108, v109, v120, s[0:1]
	v_mul_f32_e32 v109, 0x37800000, v108
	v_cndmask_b32_e32 v108, v108, v109, vcc
	v_cmp_class_f32_e32 vcc, v22, v250
	s_nop 1
	v_cndmask_b32_e32 v108, v108, v22, vcc
	v_div_scale_f32 v109, s[0:1], v108, v108, 1.0
	v_rcp_f32_e32 v120, v109
	s_mov_b32 s0, 0xbf00000
	v_lshlrev_b32_e32 v22, 16, v20
	v_and_b32_e32 v20, 0xffff0000, v20
	v_fma_f32 v121, -v109, v120, 1.0
	v_fmac_f32_e32 v120, v121, v120
	v_div_scale_f32 v121, vcc, 1.0, v108, 1.0
	v_mul_f32_e32 v122, v121, v120
	v_fma_f32 v123, -v109, v122, v121
	v_fmac_f32_e32 v122, v123, v120
	v_fma_f32 v109, -v109, v122, v121
	v_div_fmas_f32 v109, v109, v120, v122
	v_div_fixup_f32 v120, v109, v108, 1.0
	v_lshl_add_u64 v[108:109], s[42:43], 0, v[54:55]
	v_mul_f32_e32 v113, v120, v113
	v_mul_f32_e32 v113, v34, v113
	v_mul_f32_e32 v116, v120, v116
	v_add_co_u32_e32 v108, vcc, s0, v108
	v_mul_f32_e32 v116, v35, v116
	v_cvt_pk_bf16_f32 v113, v113, v116
	s_nop 0
	v_addc_co_u32_e32 v109, vcc, 0, v109, vcc
	global_store_dword v[108:109], v113, off
	v_mul_f32_e32 v113, v120, v117
	v_mul_f32_e32 v116, v120, v118
	v_mul_f32_e32 v113, v32, v113
	v_mul_f32_e32 v116, v33, v116
	v_cvt_pk_bf16_f32 v113, v113, v116
	v_pk_mul_f32 v[116:117], v[20:21], v[20:21]
	global_store_dword v[108:109], v113, off offset:256
	v_pk_fma_f32 v[116:117], v[22:23], v[22:23], v[116:117]
	v_mul_f32_e32 v95, v120, v95
	v_add_f32_e32 v113, v116, v117
	v_mul_f32_e32 v95, v31, v95
	s_nop 0
	v_add_f32_dpp v113, v113, v113 quad_perm:[1,0,3,2] row_mask:0xf bank_mask:0xf bound_ctrl:1
	s_nop 1
	v_add_f32_dpp v113, v113, v113 quad_perm:[2,3,0,1] row_mask:0xf bank_mask:0xf bound_ctrl:1
	s_nop 1
	v_add_f32_dpp v113, v113, v113 row_half_mirror row_mask:0xf bank_mask:0xf bound_ctrl:1
	s_nop 1
	v_add_f32_dpp v113, v113, v113 row_mirror row_mask:0xf bank_mask:0xf bound_ctrl:1
	s_nop 0
	v_readlane_b32 s5, v113, 16
	v_readlane_b32 s26, v113, 48
	v_readlane_b32 s0, v113, 0
	v_readlane_b32 s1, v113, 32
	v_mov_b32_e32 v116, s5
	v_mov_b32_e32 v117, s26
	v_pk_add_f32 v[116:117], s[0:1], v[116:117]
	s_nop 0
	v_add_f32_e32 v113, v116, v117
	v_fmamk_f32 v113, v113, 0x3b800000, v218
	v_mul_f32_e32 v117, v120, v119
	v_mul_f32_e32 v117, v30, v117
	v_cvt_pk_bf16_f32 v95, v117, v95
	global_store_dword v[108:109], v95, off offset:512
	v_mov_b32_e32 v117, v20
	v_mov_b32_e32 v20, v23
	s_nop 1
	s_nop 1
	s_nop 0
	v_rsq_f32_e32 v108, v113
	s_nop 0
	v_mov_b32_e32 v116, v22
	v_pk_mul_f32 v[116:117], v[108:109], v[116:117] op_sel_hi:[0,1]
	v_pk_mul_f32 v[20:21], v[108:109], v[20:21] op_sel_hi:[0,1]
	v_pk_mul_f32 v[22:23], v[2:3], v[20:21]
	s_andn2_b64 vcc, exec, s[62:63]
	v_pk_mul_f32 v[20:21], v[0:1], v[116:117]
	s_cbranch_vccnz .LBB0_197
	s_ashr_i32 s0, s11, 6
	s_and_b32 s0, s0, -4
	s_add_i32 s0, s0, s8
	s_ashr_i32 s1, s0, 31
	s_lshl_b64 s[0:1], s[0:1], 18
	v_readlane_b32 s5, v252, 9
	s_add_u32 s0, s5, s0
	v_readlane_b32 s5, v252, 10
	s_addc_u32 s1, s5, s1
	s_lshl_b32 s5, s64, 10
	s_add_u32 s0, s0, s5
	s_addc_u32 s1, s1, 0
	v_lshl_add_u64 v[108:109], v[26:27], 2, s[0:1]
	global_store_dwordx4 v[108:109], v[20:23], off nt

.LBB0_205:
	s_waitcnt lgkmcnt(0)
	v_lshlrev_b32_e32 v109, 16, v115
	v_and_b32_e32 v108, 0xffff0000, v115
	v_lshlrev_b32_e32 v82, 16, v114
	v_and_b32_e32 v80, 0xffff0000, v114
	v_lshlrev_b32_e32 v23, 16, v107
	v_lshlrev_b32_e32 v22, 16, v106
	v_and_b32_e32 v21, 0xffff0000, v107
	v_and_b32_e32 v20, 0xffff0000, v106
	v_lshlrev_b32_e32 v106, 16, v102
	v_and_b32_e32 v107, 0xffff0000, v102
	v_lshlrev_b32_e32 v114, 16, v100
	v_and_b32_e32 v115, 0xffff0000, v100
	v_lshlrev_b32_e32 v117, 16, v104
	v_lshlrev_b32_e32 v118, 16, v101
	v_and_b32_e32 v119, 0xffff0000, v101
	v_pk_mul_f32 v[100:101], v[106:107], v[114:115]
	v_lshl_add_u64 v[106:107], s[42:43], 0, v[50:51]
	v_cvt_pk_bf16_f32 v114, v116, v81
	global_store_short v[106:107], v114, off
	v_mul_f32_e32 v106, 0x3d372713, v117
	v_mul_f32_e32 v106, v106, v117
	v_fma_f32 v106, v106, v117, v117
	v_mul_f32_e32 v106, 0x3f4c422a, v106
	v_mul_f32_e32 v106, -2.0, v106
	v_mul_f32_e32 v106, 0x3fb8aa3b, v106
	v_exp_f32_e32 v106, v106
	v_lshlrev_b32_e32 v102, 16, v103
	v_and_b32_e32 v103, 0xffff0000, v103
	v_pk_mul_f32 v[102:103], v[102:103], v[118:119]
	v_add_f32_e32 v106, 1.0, v106
	v_div_scale_f32 v107, s[0:1], v106, v106, v117
	v_rcp_f32_e32 v114, v107
	v_and_b32_e32 v120, 0xffff0000, v104
	v_lshlrev_b32_e32 v121, 16, v105
	v_and_b32_e32 v122, 0xffff0000, v105
	v_fma_f32 v115, -v107, v114, 1.0
	v_fmac_f32_e32 v114, v115, v114
	v_div_scale_f32 v115, vcc, v117, v106, v117
	v_mul_f32_e32 v116, v115, v114
	v_fma_f32 v118, -v107, v116, v115
	v_fmac_f32_e32 v116, v118, v114
	v_fma_f32 v107, -v107, v116, v115
	v_div_fmas_f32 v107, v107, v114, v116
	v_div_fixup_f32 v106, v107, v106, v117
	v_mul_f32_e32 v107, 0x3d372713, v120
	v_mul_f32_e32 v107, v107, v120
	v_fma_f32 v107, v107, v120, v120
	v_mul_f32_e32 v107, 0x3f4c422a, v107
	v_mul_f32_e32 v107, -2.0, v107
	v_mul_f32_e32 v107, 0x3fb8aa3b, v107
	v_exp_f32_e32 v107, v107
	v_lshlrev_b32_e32 v123, 16, v96
	v_and_b32_e32 v124, 0xffff0000, v96
	v_lshlrev_b32_e32 v104, 16, v97
	v_add_f32_e32 v107, 1.0, v107
	v_div_scale_f32 v114, s[0:1], v107, v107, v120
	v_rcp_f32_e32 v115, v114
	v_and_b32_e32 v105, 0xffff0000, v97
	v_pk_mul_f32 v[88:89], v[10:11], v[88:89]
	v_pk_mul_f32 v[90:91], v[8:9], v[90:91]
	v_fma_f32 v116, -v114, v115, 1.0
	v_fmac_f32_e32 v115, v116, v115
	v_div_scale_f32 v116, vcc, v120, v107, v120
	v_mul_f32_e32 v117, v116, v115
	v_fma_f32 v118, -v114, v117, v116
	v_fmac_f32_e32 v117, v118, v115
	v_fma_f32 v114, -v114, v117, v116
	v_div_fmas_f32 v114, v114, v115, v117
	v_div_fixup_f32 v107, v114, v107, v120
	v_mul_f32_e32 v114, 0x3d372713, v121
	v_mul_f32_e32 v114, v114, v121
	v_fma_f32 v114, v114, v121, v121
	v_mul_f32_e32 v114, 0x3f4c422a, v114
	v_mul_f32_e32 v114, -2.0, v114
	v_mul_f32_e32 v114, 0x3fb8aa3b, v114
	v_exp_f32_e32 v114, v114
	v_cvt_pk_bf16_f32 v106, v106, v107
	v_pk_fma_f32 v[88:89], v[14:15], v[102:103], v[88:89]
	v_pk_fma_f32 v[90:91], v[12:13], v[100:101], v[90:91]
	v_add_f32_e32 v114, 1.0, v114
	v_div_scale_f32 v115, s[0:1], v114, v114, v121
	v_rcp_f32_e32 v116, v115
	v_lshlrev_b32_e32 v96, 16, v98
	v_and_b32_e32 v97, 0xffff0000, v98
	v_lshlrev_b32_e32 v98, 16, v99
	v_fma_f32 v117, -v115, v116, 1.0
	v_fmac_f32_e32 v116, v117, v116
	v_div_scale_f32 v117, vcc, v121, v114, v121
	v_mul_f32_e32 v118, v117, v116
	v_fma_f32 v119, -v115, v118, v117
	v_fmac_f32_e32 v118, v119, v116
	v_fma_f32 v115, -v115, v118, v117
	v_div_fmas_f32 v115, v115, v116, v118
	v_div_fixup_f32 v114, v115, v114, v121
	v_mul_f32_e32 v115, 0x3d372713, v122
	v_mul_f32_e32 v115, v115, v122
	v_fma_f32 v115, v115, v122, v122
	v_mul_f32_e32 v115, 0x3f4c422a, v115
	v_mul_f32_e32 v115, -2.0, v115
	v_mul_f32_e32 v115, 0x3fb8aa3b, v115
	v_exp_f32_e32 v115, v115
	v_and_b32_e32 v99, 0xffff0000, v99
	v_pk_fma_f32 v[86:87], v[16:17], v[86:87], v[90:91]
	v_pk_fma_f32 v[88:89], v[18:19], v[92:93], v[88:89]
	v_add_f32_e32 v115, 1.0, v115
	v_div_scale_f32 v116, s[0:1], v115, v115, v122
	v_rcp_f32_e32 v117, v116
	s_mov_b32 s0, 0xd100000
	v_pk_mul_f32 v[88:89], v[88:89], v[98:99]
	v_pk_mul_f32 v[86:87], v[86:87], v[96:97]
	v_fma_f32 v118, -v116, v117, 1.0
	v_fmac_f32_e32 v117, v118, v117
	v_div_scale_f32 v118, vcc, v122, v115, v122
	v_mul_f32_e32 v119, v118, v117
	v_fma_f32 v120, -v116, v119, v118
	v_fmac_f32_e32 v119, v120, v117
	v_fma_f32 v116, -v116, v119, v118
	v_div_fmas_f32 v116, v116, v117, v119
	v_div_fixup_f32 v115, v116, v115, v122
	v_cvt_pk_bf16_f32 v107, v114, v115
	v_add_co_u32_e32 v114, vcc, s0, v94
	v_lshlrev_b32_e32 v113, 16, v112
	s_nop 0
	v_addc_co_u32_e32 v115, vcc, 0, v95, vcc
	global_store_dwordx2 v[114:115], v[106:107], off
	v_mul_f32_e32 v106, 0x3d372713, v123
	v_mul_f32_e32 v107, 0x3d372713, v124
	v_mul_f32_e32 v106, v106, v123
	v_mul_f32_e32 v107, v107, v124
	v_fma_f32 v106, v106, v123, v123
	v_fma_f32 v107, v107, v124, v124
	v_mul_f32_e32 v106, 0x3f4c422a, v106
	v_mul_f32_e32 v107, 0x3f4c422a, v107
	v_mul_f32_e32 v106, -2.0, v106
	v_mul_f32_e32 v107, -2.0, v107
	v_mul_f32_e32 v106, 0x3fb8aa3b, v106
	v_mul_f32_e32 v107, 0x3fb8aa3b, v107
	v_exp_f32_e32 v106, v106
	v_exp_f32_e32 v107, v107
	v_and_b32_e32 v112, 0xffff0000, v112
	v_pk_add_f32 v[106:107], v[106:107], 1.0 op_sel_hi:[1,0]
	s_nop 0
	v_div_scale_f32 v114, s[0:1], v107, v107, v124
	v_rcp_f32_e32 v115, v114
	s_nop 0
	v_fma_f32 v116, -v114, v115, 1.0
	v_fmac_f32_e32 v115, v116, v115
	v_div_scale_f32 v116, vcc, v124, v107, v124
	v_mul_f32_e32 v117, v116, v115
	v_fma_f32 v118, -v114, v117, v116
	v_fmac_f32_e32 v117, v118, v115
	v_fma_f32 v114, -v114, v117, v116
	v_div_fmas_f32 v114, v114, v115, v117
	v_div_fixup_f32 v107, v114, v107, v124
	v_div_scale_f32 v114, s[0:1], v106, v106, v123
	v_rcp_f32_e32 v115, v114
	s_nop 0
	v_fma_f32 v116, -v114, v115, 1.0
	v_fmac_f32_e32 v115, v116, v115
	v_div_scale_f32 v116, vcc, v123, v106, v123
	v_mul_f32_e32 v117, v116, v115
	v_fma_f32 v118, -v114, v117, v116
	v_fmac_f32_e32 v117, v118, v115
	v_fma_f32 v114, -v114, v117, v116
	v_div_fmas_f32 v114, v114, v115, v117
	v_div_fixup_f32 v106, v114, v106, v123
	v_mul_f32_e32 v114, 0x3d372713, v104
	v_mul_f32_e32 v115, 0x3d372713, v105
	v_mul_f32_e32 v114, v114, v104
	v_mul_f32_e32 v115, v115, v105
	v_fma_f32 v114, v114, v104, v104
	v_fma_f32 v115, v115, v105, v105
	v_mul_f32_e32 v114, 0x3f4c422a, v114
	v_mul_f32_e32 v115, 0x3f4c422a, v115
	v_mul_f32_e32 v114, -2.0, v114
	v_mul_f32_e32 v115, -2.0, v115
	v_mul_f32_e32 v114, 0x3fb8aa3b, v114
	v_mul_f32_e32 v115, 0x3fb8aa3b, v115
	v_exp_f32_e32 v114, v114
	v_exp_f32_e32 v115, v115
	s_nop 0
	v_pk_add_f32 v[114:115], v[114:115], 1.0 op_sel_hi:[1,0]
	s_nop 0
	v_div_scale_f32 v116, s[0:1], v115, v115, v105
	v_rcp_f32_e32 v117, v116
	s_nop 0
	v_fma_f32 v118, -v116, v117, 1.0
	v_fmac_f32_e32 v117, v118, v117
	v_div_scale_f32 v118, vcc, v105, v115, v105
	v_mul_f32_e32 v119, v118, v117
	v_fma_f32 v120, -v116, v119, v118
	v_fmac_f32_e32 v119, v120, v117
	v_fma_f32 v116, -v116, v119, v118
	v_div_fmas_f32 v116, v116, v117, v119
	v_div_fixup_f32 v105, v116, v115, v105
	v_div_scale_f32 v115, s[0:1], v114, v114, v104
	v_rcp_f32_e32 v116, v115
	s_nop 0
	v_fma_f32 v117, -v115, v116, 1.0
	v_fmac_f32_e32 v116, v117, v116
	v_div_scale_f32 v117, vcc, v104, v114, v104
	v_mul_f32_e32 v118, v117, v116
	v_fma_f32 v119, -v115, v118, v117
	v_fmac_f32_e32 v118, v119, v116
	v_fma_f32 v115, -v115, v118, v117
	v_div_fmas_f32 v115, v115, v116, v118
	v_div_fixup_f32 v104, v115, v114, v104
	v_mov_b32_e32 v116, v107
	v_mov_b32_e32 v117, v105
	v_mov_b32_e32 v114, v106
	v_mov_b32_e32 v115, v104
	v_pk_mul_f32 v[116:117], v[116:117], v[116:117]
	s_nop 0
	v_pk_fma_f32 v[114:115], v[114:115], v[114:115], v[116:117]
	s_nop 0
	v_add_f32_e32 v114, v114, v115
	s_nop 1
	v_add_f32_dpp v114, v114, v114 quad_perm:[1,0,3,2] row_mask:0xf bank_mask:0xf bound_ctrl:1
	s_nop 1
	v_add_f32_dpp v114, v114, v114 quad_perm:[2,3,0,1] row_mask:0xf bank_mask:0xf bound_ctrl:1
	s_nop 1
	v_add_f32_dpp v114, v114, v114 row_half_mirror row_mask:0xf bank_mask:0xf bound_ctrl:1
	s_nop 1
	v_add_f32_dpp v114, v114, v114 row_mirror row_mask:0xf bank_mask:0xf bound_ctrl:1
	s_nop 0
	v_readlane_b32 s26, v114, 16
	v_readlane_b32 s27, v114, 48
	v_readlane_b32 s0, v114, 0
	v_readlane_b32 s1, v114, 32
	v_mov_b32_e32 v114, s26
	v_mov_b32_e32 v115, s27
	v_pk_add_f32 v[114:115], s[0:1], v[114:115]
	s_nop 0
	v_add_f32_e32 v114, v114, v115
	v_fmamk_f32 v114, v114, 0x3b800000, v218
	s_nop 0
	s_nop 0
	s_nop 0
	s_nop 1
	s_nop 1
	s_mov_b32 s0, 0xd700000
	v_rsq_f32_e32 v114, v114
	s_nop 0
	v_pk_mul_f32 v[106:107], v[106:107], v[114:115] op_sel_hi:[1,0]
	v_add_co_u32_e32 v94, vcc, s0, v94
	v_pk_mul_f32 v[104:105], v[104:105], v[114:115] op_sel_hi:[1,0]
	v_pk_mul_f32 v[106:107], v[4:5], v[106:107]
	v_addc_co_u32_e32 v95, vcc, 0, v95, vcc
	v_pk_mul_f32 v[104:105], v[6:7], v[104:105]
	v_cvt_pk_bf16_f32 v106, v106, v107
	s_nop 0
	v_cvt_pk_bf16_f32 v107, v104, v105
	global_store_dwordx2 v[94:95], v[106:107], off
	v_cvt_pk_bf16_f32 v86, v86, v87
	v_cvt_pk_bf16_f32 v87, v88, v89
	v_lshl_add_u64 v[88:89], s[42:43], 0, v[48:49]
	global_store_dwordx2 v[88:89], v[86:87], off
	v_mul_f32_e32 v86, v112, v112
	v_mul_f32_e32 v87, v108, v108
	v_fmac_f32_e32 v86, v113, v113
	v_fmac_f32_e32 v87, v109, v109
	v_add_f32_e32 v86, v86, v87
	v_mul_f32_e32 v87, v80, v80
	v_fmac_f32_e32 v87, v82, v82
	v_add_f32_e32 v86, v86, v87
	s_nop 1
	v_add_f32_dpp v86, v86, v86 quad_perm:[1,0,3,2] row_mask:0xf bank_mask:0xf bound_ctrl:1
	s_nop 1
	v_add_f32_dpp v86, v86, v86 quad_perm:[2,3,0,1] row_mask:0xf bank_mask:0xf bound_ctrl:1
	s_nop 1
	v_add_f32_dpp v86, v86, v86 row_half_mirror row_mask:0xf bank_mask:0xf bound_ctrl:1
	s_nop 1
	v_add_f32_dpp v86, v86, v86 row_mirror row_mask:0xf bank_mask:0xf bound_ctrl:1
	s_nop 0
	v_readlane_b32 s1, v86, 16
	v_readlane_b32 s0, v86, 0
	s_nop 0
	v_mov_b32_e32 v87, s1
	v_readlane_b32 s1, v86, 48
	v_add_f32_e32 v87, s0, v87
	v_readlane_b32 s0, v86, 32
	v_mov_b32_e32 v86, s1
	s_nop 0
	v_add_f32_e32 v86, s0, v86
	v_add_f32_e32 v86, v87, v86
	v_fmamk_f32 v86, v86, 0x3b2aaaab, v218
	s_nop 0
	s_nop 0
	s_nop 0
	s_nop 1
	s_nop 1
	s_nop 0
	v_rsq_f32_e32 v88, v86
	s_nop 0
	v_mul_f32_e32 v89, v88, v113
	v_mov_b32_e32 v86, 0x300
	v_mul_f32_e32 v89, v34, v89
	v_mul_f32_e32 v90, v88, v112
	v_mad_i64_i32 v[86:87], s[0:1], s4, v86, v[36:37]
	v_mul_f32_e32 v90, v35, v90
	v_cvt_pk_bf16_f32 v89, v89, v90
	global_store_dword v[86:87], v89, off
	v_mul_f32_e32 v89, v88, v109
	v_mul_f32_e32 v80, v88, v80
	v_mul_f32_e32 v89, v32, v89
	v_mul_f32_e32 v90, v88, v108
	v_mul_f32_e32 v82, v88, v82
	v_mul_f32_e32 v80, v31, v80
	v_mul_f32_e32 v90, v33, v90
	v_cvt_pk_bf16_f32 v89, v89, v90
	global_store_dword v[86:87], v89, off offset:256
	v_mul_f32_e32 v82, v30, v82
	v_cvt_pk_bf16_f32 v80, v82, v80
	global_store_dword v[86:87], v80, off offset:512
	v_pk_mul_f32 v[86:87], v[20:21], v[20:21]
	s_nop 0
	v_pk_fma_f32 v[86:87], v[22:23], v[22:23], v[86:87]
	s_nop 0
	v_add_f32_e32 v80, v86, v87
	s_nop 1
	v_add_f32_dpp v80, v80, v80 quad_perm:[1,0,3,2] row_mask:0xf bank_mask:0xf bound_ctrl:1
	s_nop 1
	v_add_f32_dpp v80, v80, v80 quad_perm:[2,3,0,1] row_mask:0xf bank_mask:0xf bound_ctrl:1
	s_nop 1
	v_add_f32_dpp v80, v80, v80 row_half_mirror row_mask:0xf bank_mask:0xf bound_ctrl:1
	s_nop 1
	v_add_f32_dpp v80, v80, v80 row_mirror row_mask:0xf bank_mask:0xf bound_ctrl:1
	s_nop 0
	v_readlane_b32 s26, v80, 16
	v_readlane_b32 s27, v80, 48
	v_readlane_b32 s0, v80, 0
	v_readlane_b32 s1, v80, 32
	v_mov_b32_e32 v86, s26
	v_mov_b32_e32 v87, s27
	v_pk_add_f32 v[86:87], s[0:1], v[86:87]
	s_nop 0
	v_add_f32_e32 v80, v86, v87
	v_fmamk_f32 v80, v80, 0x3b800000, v218
	s_nop 0
	s_nop 0
	s_nop 0
	s_nop 1
	s_nop 1
	s_nop 0
	v_rsq_f32_e32 v80, v80
	s_nop 0
	v_mov_b32_e32 v86, v22
	v_mov_b32_e32 v87, v20
	v_mov_b32_e32 v20, v23
	v_pk_mul_f32 v[86:87], v[80:81], v[86:87] op_sel_hi:[0,1]
	v_pk_mul_f32 v[20:21], v[80:81], v[20:21] op_sel_hi:[0,1]
	v_pk_mul_f32 v[22:23], v[2:3], v[20:21]
	v_pk_mul_f32 v[20:21], v[0:1], v[86:87]
	s_andn2_b64 vcc, exec, s[6:7]
	s_cbranch_vccnz .LBB0_207
	s_ashr_i32 s0, s4, 6
	s_and_b32 s0, s0, -4
	s_add_i32 s0, s0, s8
	s_ashr_i32 s1, s0, 31
	s_lshl_b64 s[0:1], s[0:1], 18
	v_readlane_b32 s6, v252, 9
	s_add_u32 s0, s6, s0
	v_readlane_b32 s6, v252, 10
	s_addc_u32 s1, s6, s1
	s_lshl_b32 s6, s18, 10
	s_add_u32 s0, s0, s6
	s_addc_u32 s1, s1, 0
	v_lshl_add_u64 v[86:87], v[26:27], 2, s[0:1]
	global_store_dwordx4 v[86:87], v[20:23], off nt

.LBB0_306:
	v_lshlrev_b32_e32 v141, 16, v115
	v_and_b32_e32 v115, 0xffff0000, v115
	v_cndmask_b32_e64 v149, v115, v47, s[36:37]
	v_cndmask_b32_e64 v148, v141, v46, s[36:37]
	v_lshlrev_b32_e32 v46, 16, v112
	v_and_b32_e32 v47, 0xffff0000, v112
	v_lshlrev_b32_e32 v112, 16, v113
	v_and_b32_e32 v113, 0xffff0000, v113
	v_cndmask_b32_e64 v155, v47, v41, s[36:37]
	v_cndmask_b32_e64 v154, v46, v40, s[36:37]
	v_lshlrev_b32_e32 v40, 16, v110
	v_and_b32_e32 v41, 0xffff0000, v110
	v_lshlrev_b32_e32 v140, 16, v114
	v_cndmask_b32_e64 v157, v113, v43, s[36:37]
	v_cndmask_b32_e64 v156, v112, v42, s[36:37]
	v_lshlrev_b32_e32 v42, 16, v111
	v_and_b32_e32 v43, 0xffff0000, v111
	v_cndmask_b32_e64 v145, v41, v37, s[36:37]
	v_cndmask_b32_e64 v144, v40, v36, s[36:37]
	v_lshlrev_b32_e32 v36, 16, v108
	v_and_b32_e32 v37, 0xffff0000, v108
	v_and_b32_e32 v114, 0xffff0000, v114
	v_cndmask_b32_e64 v44, v140, v44, s[36:37]
	v_cndmask_b32_e64 v163, v43, v39, s[36:37]
	v_cndmask_b32_e64 v162, v42, v38, s[36:37]
	v_lshlrev_b32_e32 v38, 16, v109
	v_and_b32_e32 v39, 0xffff0000, v109
	v_cndmask_b32_e64 v141, v37, v33, s[36:37]
	v_cndmask_b32_e64 v140, v36, v32, s[36:37]
	v_lshlrev_b32_e32 v32, 16, v132
	v_and_b32_e32 v33, 0xffff0000, v132
	v_cndmask_b32_e64 v45, v114, v45, s[36:37]
	v_and_b32_e32 v153, 0xffff0000, v131
	v_and_b32_e32 v152, 0xffff0000, v130
	v_cndmask_b32_e64 v143, v39, v35, s[36:37]
	v_cndmask_b32_e64 v142, v38, v34, s[36:37]
	v_lshlrev_b32_e32 v34, 16, v133
	v_and_b32_e32 v35, 0xffff0000, v133
	v_cndmask_b32_e64 v115, v33, v61, s[36:37]
	v_cndmask_b32_e64 v114, v32, v60, s[36:37]
	v_lshlrev_b32_e32 v32, 16, v128
	v_and_b32_e32 v33, 0xffff0000, v128
	v_lshlrev_b32_e32 v151, 16, v131
	v_lshlrev_b32_e32 v150, 16, v130
	v_lshlrev_b32_e32 v164, 16, v120
	v_and_b32_e32 v165, 0xffff0000, v120
	v_lshlrev_b32_e32 v166, 16, v121
	v_and_b32_e32 v167, 0xffff0000, v121
	v_cndmask_b32_e64 v121, v35, v63, s[36:37]
	v_cndmask_b32_e64 v120, v34, v62, s[36:37]
	v_lshlrev_b32_e32 v34, 16, v129
	v_and_b32_e32 v35, 0xffff0000, v129
	v_cndmask_b32_e64 v57, v33, v57, s[36:37]
	v_cndmask_b32_e64 v56, v32, v56, s[36:37]
	v_lshlrev_b32_e32 v32, 16, v124
	v_and_b32_e32 v33, 0xffff0000, v124
	v_pk_mul_f32 v[38:39], v[152:153], v[152:153]
	v_and_b32_e32 v161, 0xffff0000, v127
	v_and_b32_e32 v160, 0xffff0000, v126
	v_cndmask_b32_e64 v109, v35, v59, s[36:37]
	v_cndmask_b32_e64 v108, v34, v58, s[36:37]
	v_lshlrev_b32_e32 v34, 16, v125
	v_and_b32_e32 v35, 0xffff0000, v125
	v_cndmask_b32_e64 v37, v33, v53, s[36:37]
	v_cndmask_b32_e64 v36, v32, v52, s[36:37]
	v_lshlrev_b32_e32 v32, 16, v122
	v_and_b32_e32 v33, 0xffff0000, v122
	v_pk_fma_f32 v[38:39], v[150:151], v[150:151], v[38:39]
	v_lshlrev_b32_e32 v159, 16, v127
	v_lshlrev_b32_e32 v158, 16, v126
	v_lshlrev_b32_e32 v146, 16, v118
	v_cndmask_b32_e64 v47, v35, v55, s[36:37]
	v_cndmask_b32_e64 v46, v34, v54, s[36:37]
	v_lshlrev_b32_e32 v34, 16, v123
	v_and_b32_e32 v35, 0xffff0000, v123
	v_cndmask_b32_e64 v33, v33, v49, s[36:37]
	v_cndmask_b32_e64 v32, v32, v48, s[36:37]
	v_pk_add_f32 v[38:39], v[38:39], v[38:39] op_sel_hi:[0,1]
	v_pk_mul_f32 v[48:49], v[160:161], v[160:161]
	v_cndmask_b32_e64 v35, v35, v51, s[36:37]
	v_cndmask_b32_e64 v34, v34, v50, s[36:37]
	v_pk_fma_f32 v[48:49], v[158:159], v[158:159], v[48:49]
	v_mul_f32_e32 v147, v164, v164
	v_mul_f32_e32 v51, v165, v165
	v_mul_f32_e32 v38, v166, v166
	v_mov_b32_e32 v50, v146
	v_and_b32_e32 v42, 0xffff0000, v118
	v_lshlrev_b32_e32 v168, 16, v119
	v_and_b32_e32 v169, 0xffff0000, v119
	v_pk_add_f32 v[48:49], v[48:49], v[48:49] op_sel_hi:[0,1]
	v_pk_fma_f32 v[52:53], v[166:167], v[166:167], v[38:39] op_sel_hi:[1,1,0]
	v_pk_add_f32 v[50:51], v[146:147], v[50:51]
	v_mul_f32_e32 v52, v42, v42
	v_mul_f32_e32 v48, v168, v168
	v_mul_f32_e32 v38, v169, v169
	v_mul_f32_e32 v54, v146, v146
	v_mov_b32_e32 v55, v51
	v_pk_add_f32 v[50:51], v[54:55], v[52:53]
	v_pk_add_f32 v[38:39], v[48:49], v[38:39]
	v_and_b32_e32 v41, 0xffff0000, v116
	v_pk_add_f32 v[38:39], v[50:51], v[38:39]
	v_lshlrev_b32_e32 v43, 16, v116
	v_add_f32_e32 v38, v38, v39
	v_lshlrev_b32_e32 v122, 16, v117
	v_and_b32_e32 v123, 0xffff0000, v117
	v_add_f32_dpp v38, v38, v38 quad_perm:[1,0,3,2] row_mask:0xf bank_mask:0xf bound_ctrl:1
	v_lshlrev_b32_e32 v60, 16, v134
	v_and_b32_e32 v61, 0xffff0000, v134
	v_add_f32_dpp v38, v38, v38 quad_perm:[2,3,0,1] row_mask:0xf bank_mask:0xf bound_ctrl:1
	v_lshlrev_b32_e32 v110, 16, v135
	v_and_b32_e32 v111, 0xffff0000, v135
	v_add_f32_dpp v38, v38, v38 row_half_mirror row_mask:0xf bank_mask:0xf bound_ctrl:1
	v_lshlrev_b32_e32 v127, 16, v139
	v_lshlrev_b32_e32 v126, 16, v138
	v_add_f32_dpp v38, v38, v38 row_mirror row_mask:0xf bank_mask:0xf bound_ctrl:1
	v_and_b32_e32 v131, 0xffff0000, v139
	v_readlane_b32 s15, v38, 16
	v_readlane_b32 s26, v38, 48
	v_readlane_b32 s0, v38, 0
	v_readlane_b32 s1, v38, 32
	v_mov_b32_e32 v38, s15
	v_mov_b32_e32 v39, s26
	v_pk_add_f32 v[38:39], s[0:1], v[38:39]
	s_and_b32 s15, s7, 0xfffff000
	v_add_f32_e32 v38, v38, v39
	v_fmamk_f32 v38, v38, 0x3a800000, v218
	s_addk_i32 s15, 0x9000
	s_cmpk_gt_i32 s63, 0x1fff
	v_and_b32_e32 v130, 0xffff0000, v138
	v_lshlrev_b32_e32 v113, 16, v137
	v_lshlrev_b32_e32 v112, 16, v136
	v_and_b32_e32 v119, 0xffff0000, v137
	v_and_b32_e32 v118, 0xffff0000, v136
	v_mov_b32_e32 v147, v42
	v_mul_f32_e32 v42, v60, v60
	v_mul_f32_e32 v125, v41, v41
	s_cselect_b32 s0, s15, 0
	v_add_u32_e32 v124, s0, v80
	s_mov_b32 s0, 0x3000000
	ds_read_b128 v[48:51], v80
	ds_read_b128 v[52:55], v124 offset:8192
	v_rsq_f32_e32 v40, v38
	s_nop 0
	v_mov_b32_e32 v38, v151
	v_mov_b32_e32 v39, v153
	v_mov_b32_e32 v151, v152
	v_pk_mul_f32 v[38:39], v[40:41], v[38:39] op_sel_hi:[0,1]
	v_pk_mul_f32 v[58:59], v[40:41], v[150:151] op_sel_hi:[0,1]
	v_add_co_u32_e32 v116, vcc, s0, v66
	s_waitcnt lgkmcnt(1)
	v_pk_mul_f32 v[48:49], v[48:49], v[58:59]
	v_pk_mul_f32 v[38:39], v[50:51], v[38:39]
	v_addc_co_u32_e32 v117, vcc, 0, v67, vcc
	s_waitcnt lgkmcnt(0)
	v_pk_fma_f32 v[38:39], v[54:55], v[38:39], v[148:149]
	v_pk_fma_f32 v[44:45], v[52:53], v[48:49], v[44:45]
	v_mov_b32_e32 v58, v159
	v_cvt_pk_bf16_f32 v48, v44, v45
	v_cvt_pk_bf16_f32 v49, v38, v39
	global_store_dwordx2 v[116:117], v[48:49], off nt
	ds_read_b128 v[48:51], v80 offset:1024
	ds_read_b128 v[52:55], v124 offset:9216
	v_mov_b32_e32 v59, v161
	v_mov_b32_e32 v159, v160
	v_pk_mul_f32 v[58:59], v[40:41], v[58:59] op_sel_hi:[0,1]
	v_pk_mul_f32 v[62:63], v[40:41], v[158:159] op_sel_hi:[0,1]
	s_waitcnt lgkmcnt(1)
	v_pk_mul_f32 v[62:63], v[48:49], v[62:63]
	v_pk_mul_f32 v[48:49], v[50:51], v[58:59]
	s_waitcnt lgkmcnt(0)
	v_pk_fma_f32 v[50:51], v[52:53], v[62:63], v[154:155]
	v_pk_fma_f32 v[48:49], v[54:55], v[48:49], v[156:157]
	v_cvt_pk_bf16_f32 v58, v50, v51
	v_pk_mul_f32 v[62:63], v[40:41], v[164:165] op_sel_hi:[0,1]
	v_cvt_pk_bf16_f32 v59, v48, v49
	ds_read_b128 v[52:55], v80 offset:2048
	ds_read_b128 v[132:135], v124 offset:10240
	global_store_dwordx2 v[116:117], v[58:59], off offset:512 nt
	v_pk_mul_f32 v[58:59], v[40:41], v[166:167] op_sel_hi:[0,1]
	s_waitcnt lgkmcnt(1)
	v_pk_mul_f32 v[62:63], v[62:63], v[52:53]
	v_pk_mul_f32 v[52:53], v[58:59], v[54:55]
	s_waitcnt lgkmcnt(0)
	v_pk_fma_f32 v[54:55], v[132:133], v[62:63], v[144:145]
	v_pk_fma_f32 v[52:53], v[134:135], v[52:53], v[162:163]
	v_cvt_pk_bf16_f32 v58, v54, v55
	v_pk_mul_f32 v[62:63], v[40:41], v[146:147] op_sel_hi:[0,1]
	v_cvt_pk_bf16_f32 v59, v52, v53
	global_store_dwordx2 v[116:117], v[58:59], off offset:1024 nt
	ds_read_b128 v[132:135], v80 offset:3072
	ds_read_b128 v[136:139], v124 offset:11264
	v_pk_mul_f32 v[58:59], v[40:41], v[168:169] op_sel_hi:[0,1]
	v_mul_f32_e32 v40, v111, v111
	s_waitcnt lgkmcnt(1)
	v_pk_mul_f32 v[62:63], v[62:63], v[132:133]
	v_pk_mul_f32 v[58:59], v[58:59], v[134:135]
	s_waitcnt lgkmcnt(0)
	v_pk_fma_f32 v[62:63], v[136:137], v[62:63], v[140:141]
	v_pk_fma_f32 v[58:59], v[138:139], v[58:59], v[142:143]
	v_cvt_pk_bf16_f32 v128, v62, v63
	v_mul_f32_e32 v132, v61, v61
	v_cvt_pk_bf16_f32 v129, v58, v59
	global_store_dwordx2 v[116:117], v[128:129], off offset:1536 nt
	v_pk_mul_f32 v[116:117], v[130:131], v[130:131]
	v_pk_mul_f32 v[128:129], v[118:119], v[118:119]
	v_mov_b32_e32 v133, v43
	v_pk_fma_f32 v[116:117], v[126:127], v[126:127], v[116:117]
	v_pk_fma_f32 v[128:129], v[112:113], v[112:113], v[128:129]
	v_pk_add_f32 v[132:133], v[42:43], v[132:133]
	v_pk_mul_f32 v[134:135], v[42:43], v[42:43]
	v_mul_f32_e32 v136, v122, v122
	v_mul_f32_e32 v137, v123, v123
	v_mov_b32_e32 v133, v135
	v_pk_fma_f32 v[134:135], v[110:111], v[110:111], v[40:41] op_sel_hi:[1,1,0]
	v_pk_add_f32 v[128:129], v[128:129], v[128:129] op_sel:[0,1] op_sel_hi:[1,0]
	v_pk_add_f32 v[116:117], v[116:117], v[116:117] op_sel:[0,1] op_sel_hi:[1,0]
	v_mov_b32_e32 v135, v125
	v_mov_b32_e32 v129, v136
	v_mov_b32_e32 v117, v137
	v_pk_add_f32 v[132:133], v[132:133], v[134:135]
	v_pk_add_f32 v[116:117], v[128:129], v[116:117]
	s_nop 0
	v_pk_add_f32 v[116:117], v[132:133], v[116:117]
	s_nop 0
	v_add_f32_e32 v40, v116, v117
	s_nop 1
	v_add_f32_dpp v40, v40, v40 quad_perm:[1,0,3,2] row_mask:0xf bank_mask:0xf bound_ctrl:1
	s_nop 1
	v_add_f32_dpp v40, v40, v40 quad_perm:[2,3,0,1] row_mask:0xf bank_mask:0xf bound_ctrl:1
	s_nop 1
	v_add_f32_dpp v40, v40, v40 row_half_mirror row_mask:0xf bank_mask:0xf bound_ctrl:1
	s_nop 1
	v_add_f32_dpp v40, v40, v40 row_mirror row_mask:0xf bank_mask:0xf bound_ctrl:1
	s_nop 0
	v_readlane_b32 s15, v40, 16
	v_readlane_b32 s26, v40, 48
	v_readlane_b32 s0, v40, 0
	v_readlane_b32 s1, v40, 32
	v_mov_b32_e32 v116, s15
	v_mov_b32_e32 v117, s26
	v_pk_add_f32 v[116:117], s[0:1], v[116:117]
	s_add_i32 s0, s18, s7
	v_add_f32_e32 v40, v116, v117
	v_fmamk_f32 v40, v40, 0x3a800000, v218
	s_and_b32 s15, s0, 0xfffff000
	s_add_i32 s26, s9, s63
	s_addk_i32 s15, 0x9000
	s_cmpk_gt_i32 s26, 0x1fff
	s_mov_b32 s63, s14
	s_nop 0
	s_nop 1
	s_nop 1
	s_cselect_b32 s0, s15, 0
	s_ashr_i32 s27, s26, 31
	s_lshl_b64 s[34:35], s[26:27], 11
	v_add_u32_e32 v125, s0, v80
	ds_read_b128 v[132:135], v80
	ds_read_b128 v[136:139], v125 offset:8192
	v_rsq_f32_e32 v42, v40
	s_nop 0
	v_mov_b32_e32 v116, v127
	v_mov_b32_e32 v117, v131
	v_mov_b32_e32 v127, v130
	v_pk_mul_f32 v[116:117], v[42:43], v[116:117] op_sel_hi:[0,1]
	v_pk_mul_f32 v[126:127], v[42:43], v[126:127] op_sel_hi:[0,1]
	s_waitcnt lgkmcnt(1)
	v_pk_mul_f32 v[126:127], v[132:133], v[126:127]
	v_pk_mul_f32 v[116:117], v[134:135], v[116:117]
	v_lshl_add_u64 v[134:135], v[70:71], 0, s[34:35]
	s_waitcnt lgkmcnt(0)
	v_pk_fma_f32 v[116:117], v[138:139], v[116:117], v[120:121]
	v_pk_fma_f32 v[114:115], v[136:137], v[126:127], v[114:115]
	v_pk_mul_f32 v[110:111], v[42:43], v[110:111] op_sel_hi:[0,1]
	v_cvt_pk_bf16_f32 v120, v114, v115
	v_cvt_pk_bf16_f32 v121, v116, v117
	global_store_dwordx2 v[134:135], v[120:121], off nt
	ds_read_b128 v[126:129], v80 offset:1024
	ds_read_b128 v[130:133], v125 offset:9216
	v_mov_b32_e32 v120, v113
	v_mov_b32_e32 v121, v119
	v_mov_b32_e32 v113, v118
	v_pk_mul_f32 v[120:121], v[42:43], v[120:121] op_sel_hi:[0,1]
	v_pk_mul_f32 v[112:113], v[42:43], v[112:113] op_sel_hi:[0,1]
	s_waitcnt lgkmcnt(1)
	v_pk_mul_f32 v[112:113], v[126:127], v[112:113]
	v_pk_mul_f32 v[118:119], v[128:129], v[120:121]
	s_waitcnt lgkmcnt(0)
	v_pk_fma_f32 v[56:57], v[130:131], v[112:113], v[56:57]
	v_pk_fma_f32 v[108:109], v[132:133], v[118:119], v[108:109]
	v_cvt_pk_bf16_f32 v112, v56, v57
	v_pk_mul_f32 v[60:61], v[42:43], v[60:61] op_sel_hi:[0,1]
	v_cvt_pk_bf16_f32 v113, v108, v109
	ds_read_b128 v[118:121], v80 offset:2048
	ds_read_b128 v[126:129], v125 offset:10240
	global_store_dwordx2 v[134:135], v[112:113], off offset:512 nt
	v_mov_b32_e32 v40, v43
	v_pk_mul_f32 v[40:41], v[42:43], v[40:41] op_sel_hi:[0,1]
	s_waitcnt lgkmcnt(1)
	v_pk_mul_f32 v[60:61], v[60:61], v[118:119]
	v_pk_mul_f32 v[110:111], v[110:111], v[120:121]
	s_waitcnt lgkmcnt(0)
	v_pk_fma_f32 v[36:37], v[126:127], v[60:61], v[36:37]
	v_pk_fma_f32 v[46:47], v[128:129], v[110:111], v[46:47]
	v_cvt_pk_bf16_f32 v60, v36, v37
	s_add_i32 s7, s7, s62
	v_cvt_pk_bf16_f32 v61, v46, v47
	global_store_dwordx2 v[134:135], v[60:61], off offset:1024 nt
	ds_read_b128 v[110:113], v80 offset:3072
	ds_read_b128 v[118:121], v125 offset:11264
	v_pk_mul_f32 v[60:61], v[42:43], v[122:123] op_sel_hi:[0,1]
	v_pk_mul_f32 v[42:43], v[38:39], v[38:39]
	s_waitcnt vmcnt(9)
	v_mov_b64_e32 v[136:137], v[104:105]
	s_waitcnt lgkmcnt(1)
	v_pk_mul_f32 v[40:41], v[40:41], v[110:111]
	v_pk_mul_f32 v[110:111], v[44:45], v[44:45]
	s_waitcnt lgkmcnt(0)
	v_pk_fma_f32 v[32:33], v[118:119], v[40:41], v[32:33]
	v_pk_mov_b32 v[122:123], v[110:111], v[42:43] op_sel:[1,0]
	v_mov_b32_e32 v111, v43
	v_pk_add_f32 v[42:43], v[122:123], v[110:111]
	v_pk_mul_f32 v[110:111], v[50:51], v[50:51]
	v_pk_mul_f32 v[122:123], v[48:49], v[48:49]
	v_pk_add_f32 v[42:43], v[42:43], v[42:43] op_sel:[0,1] op_sel_hi:[1,0]
	v_pk_mov_b32 v[126:127], v[110:111], v[122:123] op_sel:[1,0]
	v_mov_b32_e32 v111, v123
	v_pk_add_f32 v[110:111], v[126:127], v[110:111]
	v_mul_f32_e32 v122, v62, v62
	v_mul_f32_e32 v123, v63, v63
	v_pk_add_f32 v[110:111], v[110:111], v[110:111] op_sel:[0,1] op_sel_hi:[1,0]
	v_mov_b32_e32 v43, v122
	v_mov_b32_e32 v111, v123
	v_pk_add_f32 v[42:43], v[42:43], v[110:111]
	v_mul_f32_e32 v110, v55, v55
	v_mul_f32_e32 v122, v53, v53
	v_mul_f32_e32 v126, v58, v58
	v_mul_f32_e32 v127, v59, v59
	v_pk_fma_f32 v[110:111], v[54:55], v[54:55], v[110:111] op_sel_hi:[1,1,0]
	v_pk_fma_f32 v[122:123], v[52:53], v[52:53], v[122:123] op_sel_hi:[1,1,0]
	v_mov_b32_e32 v111, v126
	v_mov_b32_e32 v123, v127
	v_pk_add_f32 v[110:111], v[110:111], v[122:123]
	v_mov_b64_e32 v[138:139], v[102:103]
	v_pk_add_f32 v[42:43], v[42:43], v[110:111]
	v_mov_b64_e32 v[126:127], v[86:87]
	v_add_f32_e32 v42, v42, v43
	v_mov_b64_e32 v[130:131], v[84:85]
	v_mov_b64_e32 v[132:133], v[92:93]
	v_add_f32_dpp v42, v42, v42 quad_perm:[1,0,3,2] row_mask:0xf bank_mask:0xf bound_ctrl:1
	v_mov_b64_e32 v[128:129], v[94:95]
	v_mov_b64_e32 v[122:123], v[98:99]
	v_add_f32_dpp v42, v42, v42 quad_perm:[2,3,0,1] row_mask:0xf bank_mask:0xf bound_ctrl:1
	s_nop 1
	v_add_f32_dpp v42, v42, v42 row_half_mirror row_mask:0xf bank_mask:0xf bound_ctrl:1
	s_nop 1
	v_add_f32_dpp v42, v42, v42 row_mirror row_mask:0xf bank_mask:0xf bound_ctrl:1
	s_nop 0
	v_readlane_b32 s15, v42, 16
	v_readlane_b32 s26, v42, 48
	v_readlane_b32 s0, v42, 0
	v_readlane_b32 s1, v42, 32
	v_mov_b32_e32 v42, s15
	v_mov_b32_e32 v43, s26
	v_pk_add_f32 v[42:43], s[0:1], v[42:43]
	s_nop 0
	v_add_f32_e32 v42, v42, v43
	v_fmamk_f32 v42, v42, 0x3a800000, v218
	s_nop 1
	v_rsq_f32_e32 v110, v42
	v_pk_mul_f32 v[42:43], v[60:61], v[112:113]
	v_pk_fma_f32 v[34:35], v[120:121], v[42:43], v[34:35]
	s_nop 1
	s_nop 1
	v_cvt_pk_bf16_f32 v40, v32, v33
	v_cvt_pk_bf16_f32 v41, v34, v35
	global_store_dwordx2 v[134:135], v[40:41], off offset:1536 nt
	v_mov_b32_e32 v60, v110
	ds_read_b128 v[40:43], v80 offset:4096
	ds_read_b128 v[110:113], v124 offset:28672
	ds_read_b128 v[118:121], v124 offset:49152
	v_pk_mul_f32 v[44:45], v[44:45], v[60:61] op_sel_hi:[1,0]
	v_pk_mul_f32 v[38:39], v[38:39], v[60:61] op_sel_hi:[1,0]
	s_waitcnt lgkmcnt(2)
	v_pk_mul_f32 v[40:41], v[40:41], v[44:45]
	s_waitcnt lgkmcnt(1)
	v_pk_add_f32 v[44:45], v[110:111], 1.0 op_sel_hi:[1,0]
	v_pk_mul_f32 v[38:39], v[42:43], v[38:39]
	v_pk_add_f32 v[42:43], v[112:113], 1.0 op_sel_hi:[1,0]
	s_waitcnt lgkmcnt(0)
	v_pk_fma_f32 v[40:41], v[44:45], v[40:41], v[118:119]
	v_pk_fma_f32 v[38:39], v[42:43], v[38:39], v[120:121]
	v_cvt_pk_bf16_f32 v40, v40, v41
	v_pk_mul_f32 v[50:51], v[50:51], v[60:61] op_sel_hi:[1,0]
	v_cvt_pk_bf16_f32 v41, v38, v39
	global_store_dwordx2 v[66:67], v[40:41], off
	ds_read_b128 v[38:41], v80 offset:5120
	ds_read_b128 v[42:45], v124 offset:29696
	ds_read_b128 v[110:113], v124 offset:50176
	v_pk_mul_f32 v[48:49], v[48:49], v[60:61] op_sel_hi:[1,0]
	v_pk_mul_f32 v[54:55], v[54:55], v[60:61] op_sel_hi:[1,0]
	s_waitcnt lgkmcnt(2)
	v_pk_mul_f32 v[38:39], v[38:39], v[50:51]
	s_waitcnt lgkmcnt(1)
	v_pk_add_f32 v[42:43], v[42:43], 1.0 op_sel_hi:[1,0]
	v_pk_mul_f32 v[40:41], v[40:41], v[48:49]
	v_pk_add_f32 v[44:45], v[44:45], 1.0 op_sel_hi:[1,0]
	s_waitcnt lgkmcnt(0)
	v_pk_fma_f32 v[38:39], v[42:43], v[38:39], v[110:111]
	v_pk_fma_f32 v[40:41], v[44:45], v[40:41], v[112:113]
	v_cvt_pk_bf16_f32 v38, v38, v39
	v_pk_mul_f32 v[52:53], v[52:53], v[60:61] op_sel_hi:[1,0]
	v_cvt_pk_bf16_f32 v39, v40, v41
	global_store_dwordx2 v[66:67], v[38:39], off offset:512
	ds_read_b128 v[38:41], v80 offset:6144
	ds_read_b128 v[42:45], v124 offset:30720
	ds_read_b128 v[48:51], v124 offset:51200
	s_waitcnt vmcnt(11)
	v_mov_b64_e32 v[134:135], v[106:107]
	v_mov_b64_e32 v[118:119], v[90:91]
	s_waitcnt lgkmcnt(2)
	v_pk_mul_f32 v[38:39], v[54:55], v[38:39]
	s_waitcnt lgkmcnt(1)
	v_pk_add_f32 v[42:43], v[42:43], 1.0 op_sel_hi:[1,0]
	v_pk_mul_f32 v[40:41], v[52:53], v[40:41]
	v_pk_add_f32 v[44:45], v[44:45], 1.0 op_sel_hi:[1,0]
	s_waitcnt lgkmcnt(0)
	v_pk_fma_f32 v[38:39], v[38:39], v[42:43], v[48:49]
	v_pk_fma_f32 v[40:41], v[40:41], v[44:45], v[50:51]
	v_cvt_pk_bf16_f32 v38, v38, v39
	v_pk_mul_f32 v[52:53], v[58:59], v[60:61] op_sel_hi:[1,0]
	v_cvt_pk_bf16_f32 v39, v40, v41
	global_store_dwordx2 v[66:67], v[38:39], off offset:1024
	ds_read_b128 v[38:41], v80 offset:7168
	ds_read_b128 v[42:45], v124 offset:31744
	ds_read_b128 v[48:51], v124 offset:52224
	v_pk_mul_f32 v[54:55], v[62:63], v[60:61] op_sel_hi:[1,0]
	v_mov_b64_e32 v[120:121], v[88:89]
	s_waitcnt lgkmcnt(2)
	v_pk_mul_f32 v[38:39], v[54:55], v[38:39]
	v_pk_mul_f32 v[40:41], v[52:53], v[40:41]
	v_pk_mul_f32 v[52:53], v[114:115], v[114:115]
	v_pk_mul_f32 v[54:55], v[116:117], v[116:117]
	s_waitcnt lgkmcnt(1)
	v_pk_add_f32 v[42:43], v[42:43], 1.0 op_sel_hi:[1,0]
	v_pk_mov_b32 v[58:59], v[52:53], v[54:55] op_sel:[1,0]
	v_mov_b32_e32 v53, v55
	v_pk_add_f32 v[52:53], v[58:59], v[52:53]
	v_pk_mul_f32 v[54:55], v[56:57], v[56:57]
	v_pk_mul_f32 v[58:59], v[108:109], v[108:109]
	v_pk_add_f32 v[52:53], v[52:53], v[52:53] op_sel:[0,1] op_sel_hi:[1,0]
	v_pk_mov_b32 v[60:61], v[54:55], v[58:59] op_sel:[1,0]
	v_mov_b32_e32 v55, v59
	v_pk_add_f32 v[54:55], v[60:61], v[54:55]
	v_mul_f32_e32 v58, v32, v32
	v_mul_f32_e32 v59, v33, v33
	v_pk_add_f32 v[54:55], v[54:55], v[54:55] op_sel:[0,1] op_sel_hi:[1,0]
	v_mov_b32_e32 v53, v58
	v_mov_b32_e32 v55, v59
	v_pk_add_f32 v[52:53], v[52:53], v[54:55]
	v_mul_f32_e32 v54, v37, v37
	v_mul_f32_e32 v58, v47, v47
	v_mul_f32_e32 v60, v34, v34
	v_mul_f32_e32 v61, v35, v35
	v_pk_fma_f32 v[54:55], v[36:37], v[36:37], v[54:55] op_sel_hi:[1,1,0]
	v_pk_fma_f32 v[58:59], v[46:47], v[46:47], v[58:59] op_sel_hi:[1,1,0]
	v_mov_b32_e32 v55, v60
	v_mov_b32_e32 v59, v61
	v_pk_add_f32 v[54:55], v[54:55], v[58:59]
	s_waitcnt lgkmcnt(0)
	v_pk_fma_f32 v[38:39], v[38:39], v[42:43], v[48:49]
	v_pk_add_f32 v[52:53], v[52:53], v[54:55]
	v_pk_add_f32 v[44:45], v[44:45], 1.0 op_sel_hi:[1,0]
	v_add_f32_e32 v52, v52, v53
	v_pk_fma_f32 v[40:41], v[40:41], v[44:45], v[50:51]
	v_cvt_pk_bf16_f32 v38, v38, v39
	v_mov_b64_e32 v[62:63], v[18:19]
	v_add_f32_dpp v52, v52, v52 quad_perm:[1,0,3,2] row_mask:0xf bank_mask:0xf bound_ctrl:1
	v_cvt_pk_bf16_f32 v39, v40, v41
	global_store_dwordx2 v[66:67], v[38:39], off offset:1536
	v_lshl_add_u64 v[66:67], v[66:67], 0, s[10:11]
	v_add_f32_dpp v52, v52, v52 quad_perm:[2,3,0,1] row_mask:0xf bank_mask:0xf bound_ctrl:1
	v_mov_b64_e32 v[112:113], v[78:79]
	v_mov_b64_e32 v[110:111], v[76:77]
	v_add_f32_dpp v52, v52, v52 row_half_mirror row_mask:0xf bank_mask:0xf bound_ctrl:1
	v_mov_b64_e32 v[60:61], v[16:17]
	s_nop 0
	v_add_f32_dpp v52, v52, v52 row_mirror row_mask:0xf bank_mask:0xf bound_ctrl:1
	s_nop 0
	v_readlane_b32 s15, v52, 16
	v_readlane_b32 s26, v52, 48
	v_readlane_b32 s0, v52, 0
	v_readlane_b32 s1, v52, 32
	v_mov_b32_e32 v52, s15
	v_mov_b32_e32 v53, s26
	v_pk_add_f32 v[52:53], s[0:1], v[52:53]
	s_nop 0
	v_add_f32_e32 v52, v52, v53
	v_fmamk_f32 v52, v52, 0x3a800000, v218
	s_nop 1
	s_nop 0
	s_nop 1
	s_nop 1
	s_nop 0
	v_rsq_f32_e32 v52, v52
	s_nop 0
	ds_read_b128 v[38:41], v80 offset:4096
	ds_read_b128 v[42:45], v125 offset:28672
	ds_read_b128 v[48:51], v125 offset:49152
	v_pk_mul_f32 v[58:59], v[114:115], v[52:53] op_sel_hi:[1,0]
	v_pk_mul_f32 v[54:55], v[116:117], v[52:53] op_sel_hi:[1,0]
	s_waitcnt lgkmcnt(2)
	v_pk_mul_f32 v[38:39], v[38:39], v[58:59]
	s_waitcnt lgkmcnt(1)
	v_pk_add_f32 v[42:43], v[42:43], 1.0 op_sel_hi:[1,0]
	v_pk_mul_f32 v[40:41], v[40:41], v[54:55]
	v_pk_add_f32 v[44:45], v[44:45], 1.0 op_sel_hi:[1,0]
	s_waitcnt lgkmcnt(0)
	v_pk_fma_f32 v[38:39], v[42:43], v[38:39], v[48:49]
	v_lshl_add_u64 v[54:55], v[64:65], 0, s[34:35]
	v_pk_fma_f32 v[40:41], v[44:45], v[40:41], v[50:51]
	v_cvt_pk_bf16_f32 v38, v38, v39
	v_pk_mul_f32 v[56:57], v[56:57], v[52:53] op_sel_hi:[1,0]
	v_cvt_pk_bf16_f32 v39, v40, v41
	global_store_dwordx2 v[54:55], v[38:39], off
	ds_read_b128 v[38:41], v80 offset:5120
	ds_read_b128 v[42:45], v125 offset:29696
	ds_read_b128 v[48:51], v125 offset:50176
	v_pk_mul_f32 v[58:59], v[108:109], v[52:53] op_sel_hi:[1,0]
	v_pk_mul_f32 v[36:37], v[36:37], v[52:53] op_sel_hi:[1,0]
	s_waitcnt lgkmcnt(2)
	v_pk_mul_f32 v[38:39], v[38:39], v[56:57]
	s_waitcnt lgkmcnt(1)
	v_pk_add_f32 v[42:43], v[42:43], 1.0 op_sel_hi:[1,0]
	v_pk_mul_f32 v[40:41], v[40:41], v[58:59]
	v_pk_add_f32 v[44:45], v[44:45], 1.0 op_sel_hi:[1,0]
	s_waitcnt lgkmcnt(0)
	v_pk_fma_f32 v[38:39], v[42:43], v[38:39], v[48:49]
	v_pk_fma_f32 v[40:41], v[44:45], v[40:41], v[50:51]
	v_cvt_pk_bf16_f32 v38, v38, v39
	v_pk_mul_f32 v[46:47], v[46:47], v[52:53] op_sel_hi:[1,0]
	v_cvt_pk_bf16_f32 v39, v40, v41
	global_store_dwordx2 v[54:55], v[38:39], off offset:512
	ds_read_b128 v[38:41], v80 offset:6144
	ds_read_b128 v[42:45], v125 offset:30720
	ds_read_b128 v[48:51], v125 offset:51200
	v_pk_mul_f32 v[34:35], v[34:35], v[52:53] op_sel_hi:[1,0]
	v_pk_mul_f32 v[32:33], v[32:33], v[52:53] op_sel_hi:[1,0]
	s_waitcnt lgkmcnt(2)
	v_pk_mul_f32 v[36:37], v[36:37], v[38:39]
	s_waitcnt lgkmcnt(1)
	v_pk_add_f32 v[42:43], v[42:43], 1.0 op_sel_hi:[1,0]
	v_pk_mul_f32 v[38:39], v[46:47], v[40:41]
	v_pk_add_f32 v[40:41], v[44:45], 1.0 op_sel_hi:[1,0]
	s_waitcnt lgkmcnt(0)
	v_pk_fma_f32 v[36:37], v[36:37], v[42:43], v[48:49]
	v_pk_fma_f32 v[38:39], v[38:39], v[40:41], v[50:51]
	v_cvt_pk_bf16_f32 v36, v36, v37
	v_mov_b64_e32 v[58:59], v[22:23]
	v_cvt_pk_bf16_f32 v37, v38, v39
	global_store_dwordx2 v[54:55], v[36:37], off offset:1024
	ds_read_b128 v[36:39], v80 offset:7168
	ds_read_b128 v[40:43], v125 offset:31744
	ds_read_b128 v[44:47], v125 offset:52224
	v_mov_b64_e32 v[50:51], v[30:31]
	s_andn2_b64 vcc, exec, s[30:31]
	s_waitcnt lgkmcnt(2)
	v_pk_mul_f32 v[32:33], v[32:33], v[36:37]
	v_pk_mul_f32 v[34:35], v[34:35], v[38:39]
	s_waitcnt lgkmcnt(1)
	v_pk_add_f32 v[38:39], v[40:41], 1.0 op_sel_hi:[1,0]
	v_pk_add_f32 v[36:37], v[42:43], 1.0 op_sel_hi:[1,0]
	s_waitcnt lgkmcnt(0)
	v_pk_fma_f32 v[32:33], v[32:33], v[38:39], v[44:45]
	v_pk_fma_f32 v[34:35], v[34:35], v[36:37], v[46:47]
	v_cvt_pk_bf16_f32 v32, v32, v33
	v_mov_b64_e32 v[46:47], v[2:3]
	v_cvt_pk_bf16_f32 v33, v34, v35
	global_store_dwordx2 v[54:55], v[32:33], off offset:1536
	v_mov_b64_e32 v[42:43], v[6:7]
	v_mov_b64_e32 v[38:39], v[10:11]
	v_mov_b64_e32 v[34:35], v[14:15]
	v_mov_b64_e32 v[54:55], v[26:27]
	s_waitcnt vmcnt(16)
	v_mov_b64_e32 v[116:117], v[100:101]
	v_mov_b64_e32 v[114:115], v[82:83]
	v_mov_b64_e32 v[108:109], v[74:75]
	v_mov_b64_e32 v[124:125], v[96:97]
	v_mov_b64_e32 v[44:45], v[0:1]
	v_mov_b64_e32 v[40:41], v[4:5]
	v_mov_b64_e32 v[36:37], v[8:9]
	v_mov_b64_e32 v[32:33], v[12:13]
	v_mov_b64_e32 v[56:57], v[20:21]
	v_mov_b64_e32 v[52:53], v[24:25]
	v_mov_b64_e32 v[48:49], v[28:29]
	s_cbranch_vccz .LBB0_316

.LBB0_343:
	v_and_b32_e32 v29, 0xffff0000, v111
	v_and_b32_e32 v28, 0xffff0000, v110
	v_lshlrev_b32_e32 v27, 16, v111
	v_lshlrev_b32_e32 v26, 16, v110
	v_pk_mul_f32 v[0:1], v[28:29], v[28:29]
	v_and_b32_e32 v7, 0xffff0000, v109
	v_and_b32_e32 v6, 0xffff0000, v108
	v_pk_fma_f32 v[0:1], v[26:27], v[26:27], v[0:1]
	v_lshlrev_b32_e32 v5, 16, v109
	v_lshlrev_b32_e32 v4, 16, v108
	v_lshlrev_b32_e32 v8, 16, v106
	v_and_b32_e32 v9, 0xffff0000, v106
	v_lshlrev_b32_e32 v10, 16, v107
	v_lshlrev_b32_e32 v12, 16, v104
	v_pk_add_f32 v[0:1], v[0:1], v[0:1] op_sel_hi:[0,1]
	v_pk_mul_f32 v[2:3], v[6:7], v[6:7]
	v_and_b32_e32 v11, 0xffff0000, v107
	v_pk_fma_f32 v[2:3], v[4:5], v[4:5], v[2:3]
	v_mul_f32_e32 v13, v8, v8
	v_mul_f32_e32 v17, v9, v9
	v_mul_f32_e32 v0, v10, v10
	v_mov_b32_e32 v16, v12
	v_and_b32_e32 v18, 0xffff0000, v104
	v_lshlrev_b32_e32 v14, 16, v105
	v_and_b32_e32 v15, 0xffff0000, v105
	v_pk_add_f32 v[2:3], v[2:3], v[2:3] op_sel_hi:[0,1]
	v_pk_fma_f32 v[20:21], v[10:11], v[10:11], v[0:1] op_sel_hi:[1,1,0]
	v_pk_add_f32 v[16:17], v[12:13], v[16:17]
	v_mul_f32_e32 v20, v18, v18
	v_mul_f32_e32 v2, v14, v14
	v_mul_f32_e32 v0, v15, v15
	v_mul_f32_e32 v22, v12, v12
	v_mov_b32_e32 v23, v17
	v_pk_add_f32 v[16:17], v[22:23], v[20:21]
	v_pk_add_f32 v[0:1], v[2:3], v[0:1]
	v_lshlrev_b32_e32 v24, 16, v102
	v_pk_add_f32 v[0:1], v[16:17], v[0:1]
	v_and_b32_e32 v25, 0xffff0000, v102
	v_add_f32_e32 v0, v0, v1
	v_mov_b32_e32 v104, v27
	v_mov_b32_e32 v105, v29
	v_add_f32_dpp v0, v0, v0 quad_perm:[1,0,3,2] row_mask:0xf bank_mask:0xf bound_ctrl:1
	v_mov_b32_e32 v27, v28
	v_lshlrev_b32_e32 v30, 16, v103
	v_add_f32_dpp v0, v0, v0 quad_perm:[2,3,0,1] row_mask:0xf bank_mask:0xf bound_ctrl:1
	v_and_b32_e32 v31, 0xffff0000, v103
	s_nop 0
	v_add_f32_dpp v0, v0, v0 row_half_mirror row_mask:0xf bank_mask:0xf bound_ctrl:1
	s_nop 1
	v_add_f32_dpp v0, v0, v0 row_mirror row_mask:0xf bank_mask:0xf bound_ctrl:1
	s_nop 0
	v_readlane_b32 s23, v0, 16
	v_readlane_b32 s26, v0, 48
	v_readlane_b32 s0, v0, 0
	v_readlane_b32 s1, v0, 32
	v_mov_b32_e32 v0, s23
	v_mov_b32_e32 v1, s26
	v_pk_add_f32 v[0:1], s[0:1], v[0:1]
	s_and_b32 s23, s11, 0xfffff000
	v_add_f32_e32 v0, v0, v1
	v_fmamk_f32 v0, v0, 0x3a800000, v218
	s_addk_i32 s23, 0x9000
	s_cmpk_gt_i32 s34, 0x1fff
	s_nop 0
	s_nop 0
	s_nop 1
	s_nop 1
	s_cselect_b32 s0, s23, 0
	v_add_u32_e32 v102, s0, v80
	s_mov_b64 s[0:1], -1
	v_rsq_f32_e32 v16, v0
	s_nop 0
	ds_read_b128 v[0:3], v80
	ds_read_b128 v[20:23], v102 offset:8192
	v_pk_mul_f32 v[104:105], v[16:17], v[104:105] op_sel_hi:[0,1]
	v_pk_mul_f32 v[26:27], v[16:17], v[26:27] op_sel_hi:[0,1]
	s_and_b64 vcc, exec, s[6:7]
	s_waitcnt lgkmcnt(1)
	v_pk_mul_f32 v[0:1], v[0:1], v[26:27]
	v_pk_mul_f32 v[2:3], v[2:3], v[104:105]
	s_waitcnt lgkmcnt(0)
	v_pk_fma_f32 v[0:1], v[20:21], v[0:1], v[24:25]
	v_pk_fma_f32 v[2:3], v[22:23], v[2:3], v[30:31]
	s_cbranch_vccz .LBB0_345
	v_add_co_u32_e32 v22, vcc, 0x3000000, v44
	v_cvt_pk_bf16_f32 v20, v0, v1
	v_cvt_pk_bf16_f32 v21, v2, v3
	s_mov_b64 s[0:1], 0
	s_nop 0
	v_addc_co_u32_e32 v23, vcc, 0, v45, vcc
	global_store_dwordx2 v[22:23], v[20:21], off nt

.LBB0_359:
	v_and_b32_e32 v105, 0xffff0000, v93
	v_and_b32_e32 v104, 0xffff0000, v92
	v_and_b32_e32 v23, 0xffff0000, v91
	v_and_b32_e32 v22, 0xffff0000, v90
	v_lshlrev_b32_e32 v24, 16, v86
	v_and_b32_e32 v25, 0xffff0000, v86
	v_lshlrev_b32_e32 v31, 16, v88
	v_lshlrev_b32_e32 v101, 16, v93
	v_lshlrev_b32_e32 v100, 16, v92
	v_lshlrev_b32_e32 v21, 16, v91
	v_lshlrev_b32_e32 v20, 16, v90
	v_lshlrev_b32_e32 v26, 16, v87
	v_and_b32_e32 v27, 0xffff0000, v87
	v_and_b32_e32 v29, 0xffff0000, v88
	v_lshlrev_b32_e32 v86, 16, v89
	v_and_b32_e32 v87, 0xffff0000, v89
	v_pk_mul_f32 v[16:17], v[104:105], v[104:105]
	v_pk_mul_f32 v[18:19], v[22:23], v[22:23]
	v_mul_f32_e32 v30, v24, v24
	v_mul_f32_e32 v88, v25, v25
	v_mov_b32_e32 v89, v31
	v_pk_fma_f32 v[16:17], v[100:101], v[100:101], v[16:17]
	v_pk_fma_f32 v[18:19], v[20:21], v[20:21], v[18:19]
	v_pk_add_f32 v[88:89], v[30:31], v[88:89]
	v_pk_mul_f32 v[90:91], v[30:31], v[30:31]
	v_mul_f32_e32 v28, v27, v27
	v_lshlrev_b32_e32 v96, 16, v94
	v_and_b32_e32 v97, 0xffff0000, v94
	v_mul_f32_e32 v92, v29, v29
	v_mul_f32_e32 v93, v86, v86
	v_mul_f32_e32 v94, v87, v87
	v_mov_b32_e32 v89, v91
	v_pk_fma_f32 v[90:91], v[26:27], v[26:27], v[28:29] op_sel_hi:[1,1,0]
	v_pk_add_f32 v[18:19], v[18:19], v[18:19] op_sel:[0,1] op_sel_hi:[1,0]
	v_pk_add_f32 v[16:17], v[16:17], v[16:17] op_sel:[0,1] op_sel_hi:[1,0]
	v_mov_b32_e32 v91, v92
	v_mov_b32_e32 v19, v93
	v_mov_b32_e32 v17, v94
	v_pk_add_f32 v[88:89], v[88:89], v[90:91]
	v_pk_add_f32 v[16:17], v[18:19], v[16:17]
	s_add_i32 s38, s9, s34
	v_pk_add_f32 v[16:17], v[88:89], v[16:17]
	v_mov_b32_e32 v106, v101
	v_add_f32_e32 v16, v16, v17
	v_mov_b32_e32 v107, v105
	v_mov_b32_e32 v101, v104
	v_add_f32_dpp v16, v16, v16 quad_perm:[1,0,3,2] row_mask:0xf bank_mask:0xf bound_ctrl:1
	v_lshlrev_b32_e32 v98, 16, v95
	v_and_b32_e32 v99, 0xffff0000, v95
	v_add_f32_dpp v16, v16, v16 quad_perm:[2,3,0,1] row_mask:0xf bank_mask:0xf bound_ctrl:1
	s_nop 1
	v_add_f32_dpp v16, v16, v16 row_half_mirror row_mask:0xf bank_mask:0xf bound_ctrl:1
	s_nop 1
	v_add_f32_dpp v16, v16, v16 row_mirror row_mask:0xf bank_mask:0xf bound_ctrl:1
	s_nop 0
	v_readlane_b32 s23, v16, 16
	v_readlane_b32 s26, v16, 48
	v_readlane_b32 s0, v16, 0
	v_readlane_b32 s1, v16, 32
	v_mov_b32_e32 v16, s23
	v_mov_b32_e32 v17, s26
	v_pk_add_f32 v[16:17], s[0:1], v[16:17]
	s_add_i32 s0, s18, s11
	v_add_f32_e32 v16, v16, v17
	v_fmamk_f32 v16, v16, 0x3a800000, v218
	s_and_b32 s23, s0, 0xfffff000
	s_addk_i32 s23, 0x9000
	s_cmpk_gt_i32 s38, 0x1fff
	s_nop 0
	s_nop 1
	s_nop 1
	s_cselect_b32 s0, s23, 0
	v_add_u32_e32 v94, s0, v80
	s_ashr_i32 s39, s38, 31
	v_rsq_f32_e32 v88, v16
	s_nop 0
	ds_read_b128 v[16:19], v80
	ds_read_b128 v[90:93], v94 offset:8192
	s_lshl_b64 s[34:35], s[38:39], 11
	s_add_u32 s26, s96, s34
	v_pk_mul_f32 v[106:107], v[88:89], v[106:107] op_sel_hi:[0,1]
	v_pk_mul_f32 v[100:101], v[88:89], v[100:101] op_sel_hi:[0,1]
	s_addc_u32 s27, s97, s35
	s_waitcnt lgkmcnt(1)
	v_pk_mul_f32 v[16:17], v[16:17], v[100:101]
	v_pk_mul_f32 v[18:19], v[18:19], v[106:107]
	s_waitcnt lgkmcnt(0)
	v_pk_fma_f32 v[16:17], v[90:91], v[16:17], v[96:97]
	v_pk_fma_f32 v[18:19], v[92:93], v[18:19], v[98:99]
	s_mov_b64 s[0:1], -1
	s_and_b64 vcc, exec, s[36:37]
	v_lshl_add_u64 v[90:91], v[36:37], 1, s[26:27]
	s_cbranch_vccnz .LBB0_361
	s_mov_b64 s[0:1], 0
	v_cvt_pk_bf16_f32 v92, v16, v17
	v_cvt_pk_bf16_f32 v93, v18, v19
	global_store_dwordx2 v[90:91], v[92:93], off nt

.LBB0_376:
	v_pk_mul_f32 v[78:79], v[2:3], v[2:3]
	v_pk_mul_f32 v[82:83], v[0:1], v[0:1]
	s_nop 0
	v_pk_mov_b32 v[84:85], v[82:83], v[78:79] op_sel:[1,0]
	v_mov_b32_e32 v83, v79
	v_pk_add_f32 v[78:79], v[84:85], v[82:83]
	v_pk_mul_f32 v[82:83], v[6:7], v[6:7]
	v_pk_mul_f32 v[84:85], v[4:5], v[4:5]
	v_pk_add_f32 v[78:79], v[78:79], v[78:79] op_sel:[0,1] op_sel_hi:[1,0]
	v_pk_mov_b32 v[86:87], v[84:85], v[82:83] op_sel:[1,0]
	v_mov_b32_e32 v85, v83
	v_pk_add_f32 v[82:83], v[86:87], v[84:85]
	v_mul_f32_e32 v84, v12, v12
	v_mul_f32_e32 v85, v13, v13
	v_pk_add_f32 v[82:83], v[82:83], v[82:83] op_sel:[0,1] op_sel_hi:[1,0]
	v_mov_b32_e32 v79, v84
	v_mov_b32_e32 v83, v85
	v_pk_add_f32 v[78:79], v[78:79], v[82:83]
	v_mul_f32_e32 v82, v9, v9
	v_mul_f32_e32 v84, v11, v11
	v_mul_f32_e32 v86, v14, v14
	v_mul_f32_e32 v87, v15, v15
	v_pk_fma_f32 v[82:83], v[8:9], v[8:9], v[82:83] op_sel_hi:[1,1,0]
	v_pk_fma_f32 v[84:85], v[10:11], v[10:11], v[84:85] op_sel_hi:[1,1,0]
	v_mov_b32_e32 v83, v86
	v_mov_b32_e32 v85, v87
	v_pk_add_f32 v[82:83], v[82:83], v[84:85]
	s_nop 0
	v_pk_add_f32 v[78:79], v[78:79], v[82:83]
	s_nop 0
	v_add_f32_e32 v78, v78, v79
	s_nop 1
	v_add_f32_dpp v78, v78, v78 quad_perm:[1,0,3,2] row_mask:0xf bank_mask:0xf bound_ctrl:1
	s_nop 1
	v_add_f32_dpp v78, v78, v78 quad_perm:[2,3,0,1] row_mask:0xf bank_mask:0xf bound_ctrl:1
	s_nop 1
	v_add_f32_dpp v78, v78, v78 row_half_mirror row_mask:0xf bank_mask:0xf bound_ctrl:1
	s_nop 1
	v_add_f32_dpp v78, v78, v78 row_mirror row_mask:0xf bank_mask:0xf bound_ctrl:1
	s_nop 0
	v_readlane_b32 s23, v78, 16
	v_readlane_b32 s26, v78, 48
	v_readlane_b32 s0, v78, 0
	v_readlane_b32 s1, v78, 32
	v_mov_b32_e32 v78, s23
	v_mov_b32_e32 v79, s26
	v_pk_add_f32 v[78:79], s[0:1], v[78:79]
	s_nop 0
	v_add_f32_e32 v78, v78, v79
	v_fmamk_f32 v78, v78, 0x3a800000, v218
	s_nop 1
	s_nop 0
	s_nop 0
	s_nop 1
	s_nop 1
	s_nop 0
	ds_read_b128 v[82:85], v80 offset:4096
	ds_read_b128 v[86:89], v102 offset:28672
	ds_read_b128 v[90:93], v102 offset:49152
	v_rsq_f32_e32 v78, v78
	s_nop 0
	v_pk_mul_f32 v[2:3], v[2:3], v[78:79] op_sel_hi:[1,0]
	v_pk_mul_f32 v[0:1], v[0:1], v[78:79] op_sel_hi:[1,0]
	s_waitcnt lgkmcnt(2)
	v_pk_mul_f32 v[2:3], v[84:85], v[2:3]
	v_pk_mul_f32 v[0:1], v[82:83], v[0:1]
	s_waitcnt lgkmcnt(1)
	v_pk_add_f32 v[84:85], v[86:87], 1.0 op_sel_hi:[1,0]
	v_pk_add_f32 v[82:83], v[88:89], 1.0 op_sel_hi:[1,0]
	s_waitcnt lgkmcnt(0)
	v_pk_fma_f32 v[0:1], v[84:85], v[0:1], v[90:91]
	v_pk_fma_f32 v[2:3], v[82:83], v[2:3], v[92:93]
	v_cvt_pk_bf16_f32 v0, v0, v1
	v_pk_mul_f32 v[6:7], v[6:7], v[78:79] op_sel_hi:[1,0]
	v_cvt_pk_bf16_f32 v1, v2, v3
	global_store_dwordx2 v[44:45], v[0:1], off
	ds_read_b128 v[0:3], v80 offset:5120
	ds_read_b128 v[82:85], v102 offset:29696
	ds_read_b128 v[86:89], v102 offset:50176
	v_pk_mul_f32 v[4:5], v[4:5], v[78:79] op_sel_hi:[1,0]
	v_pk_mul_f32 v[8:9], v[8:9], v[78:79] op_sel_hi:[1,0]
	s_waitcnt lgkmcnt(2)
	v_pk_mul_f32 v[0:1], v[0:1], v[4:5]
	v_pk_mul_f32 v[2:3], v[2:3], v[6:7]
	s_waitcnt lgkmcnt(1)
	v_pk_add_f32 v[6:7], v[82:83], 1.0 op_sel_hi:[1,0]
	v_pk_add_f32 v[4:5], v[84:85], 1.0 op_sel_hi:[1,0]
	s_waitcnt lgkmcnt(0)
	v_pk_fma_f32 v[0:1], v[6:7], v[0:1], v[86:87]
	v_pk_fma_f32 v[2:3], v[4:5], v[2:3], v[88:89]
	v_cvt_pk_bf16_f32 v0, v0, v1
	v_pk_mul_f32 v[10:11], v[10:11], v[78:79] op_sel_hi:[1,0]
	v_cvt_pk_bf16_f32 v1, v2, v3
	global_store_dwordx2 v[44:45], v[0:1], off offset:512
	ds_read_b128 v[0:3], v80 offset:6144
	ds_read_b128 v[4:7], v102 offset:30720
	ds_read_b128 v[82:85], v102 offset:51200
	v_pk_mul_f32 v[14:15], v[14:15], v[78:79] op_sel_hi:[1,0]
	v_pk_mul_f32 v[12:13], v[12:13], v[78:79] op_sel_hi:[1,0]
	s_waitcnt lgkmcnt(2)
	v_pk_mul_f32 v[0:1], v[8:9], v[0:1]
	s_waitcnt lgkmcnt(1)
	v_pk_add_f32 v[4:5], v[4:5], 1.0 op_sel_hi:[1,0]
	v_pk_mul_f32 v[2:3], v[10:11], v[2:3]
	v_pk_add_f32 v[6:7], v[6:7], 1.0 op_sel_hi:[1,0]
	s_waitcnt lgkmcnt(0)
	v_pk_fma_f32 v[0:1], v[0:1], v[4:5], v[82:83]
	v_pk_fma_f32 v[2:3], v[2:3], v[6:7], v[84:85]
	v_cvt_pk_bf16_f32 v0, v0, v1
	s_nop 0
	v_cvt_pk_bf16_f32 v1, v2, v3
	global_store_dwordx2 v[44:45], v[0:1], off offset:1024
	ds_read_b128 v[0:3], v80 offset:7168
	ds_read_b128 v[4:7], v102 offset:31744
	ds_read_b128 v[8:11], v102 offset:52224
	s_waitcnt lgkmcnt(2)
	v_pk_mul_f32 v[0:1], v[12:13], v[0:1]
	v_pk_mul_f32 v[2:3], v[14:15], v[2:3]
	v_pk_mul_f32 v[12:13], v[18:19], v[18:19]
	v_pk_mul_f32 v[14:15], v[16:17], v[16:17]
	s_waitcnt lgkmcnt(1)
	v_pk_add_f32 v[4:5], v[4:5], 1.0 op_sel_hi:[1,0]
	v_pk_mov_b32 v[78:79], v[14:15], v[12:13] op_sel:[1,0]
	v_mov_b32_e32 v15, v13
	v_pk_add_f32 v[12:13], v[78:79], v[14:15]
	v_pk_mul_f32 v[14:15], v[22:23], v[22:23]
	v_pk_mul_f32 v[78:79], v[20:21], v[20:21]
	v_pk_add_f32 v[12:13], v[12:13], v[12:13] op_sel:[0,1] op_sel_hi:[1,0]
	v_pk_mov_b32 v[82:83], v[78:79], v[14:15] op_sel:[1,0]
	v_mov_b32_e32 v79, v15
	v_pk_add_f32 v[14:15], v[82:83], v[78:79]
	v_mul_f32_e32 v78, v28, v28
	v_mul_f32_e32 v79, v29, v29
	v_pk_add_f32 v[14:15], v[14:15], v[14:15] op_sel:[0,1] op_sel_hi:[1,0]
	v_mov_b32_e32 v13, v78
	v_mov_b32_e32 v15, v79
	v_pk_add_f32 v[12:13], v[12:13], v[14:15]
	v_mul_f32_e32 v14, v25, v25
	v_mul_f32_e32 v78, v27, v27
	v_mul_f32_e32 v82, v30, v30
	v_mul_f32_e32 v83, v31, v31
	v_pk_fma_f32 v[14:15], v[24:25], v[24:25], v[14:15] op_sel_hi:[1,1,0]
	v_pk_fma_f32 v[78:79], v[26:27], v[26:27], v[78:79] op_sel_hi:[1,1,0]
	v_mov_b32_e32 v15, v82
	v_mov_b32_e32 v79, v83
	v_pk_add_f32 v[14:15], v[14:15], v[78:79]
	s_waitcnt lgkmcnt(0)
	v_pk_fma_f32 v[0:1], v[0:1], v[4:5], v[8:9]
	v_pk_add_f32 v[12:13], v[12:13], v[14:15]
	v_pk_add_f32 v[6:7], v[6:7], 1.0 op_sel_hi:[1,0]
	v_add_f32_e32 v12, v12, v13
	v_pk_fma_f32 v[2:3], v[2:3], v[6:7], v[10:11]
	v_cvt_pk_bf16_f32 v0, v0, v1
	s_nop 0
	v_add_f32_dpp v12, v12, v12 quad_perm:[1,0,3,2] row_mask:0xf bank_mask:0xf bound_ctrl:1
	v_cvt_pk_bf16_f32 v1, v2, v3
	global_store_dwordx2 v[44:45], v[0:1], off offset:1536
	s_nop 0
	v_add_f32_dpp v12, v12, v12 quad_perm:[2,3,0,1] row_mask:0xf bank_mask:0xf bound_ctrl:1
	s_nop 1
	v_add_f32_dpp v12, v12, v12 row_half_mirror row_mask:0xf bank_mask:0xf bound_ctrl:1
	s_nop 1
	v_add_f32_dpp v12, v12, v12 row_mirror row_mask:0xf bank_mask:0xf bound_ctrl:1
	s_nop 0
	v_readlane_b32 s23, v12, 16
	v_readlane_b32 s26, v12, 48
	v_readlane_b32 s0, v12, 0
	v_readlane_b32 s1, v12, 32
	v_mov_b32_e32 v12, s23
	v_mov_b32_e32 v13, s26
	v_pk_add_f32 v[12:13], s[0:1], v[12:13]
	s_nop 0
	v_add_f32_e32 v12, v12, v13
	v_fmamk_f32 v12, v12, 0x3a800000, v218
	s_nop 1
	s_nop 0
	s_nop 1
	s_nop 1
	s_nop 0
	v_rsq_f32_e32 v12, v12
	s_nop 0
	ds_read_b128 v[0:3], v80 offset:4096
	ds_read_b128 v[4:7], v94 offset:28672
	ds_read_b128 v[8:11], v94 offset:49152
	v_pk_mul_f32 v[16:17], v[16:17], v[12:13] op_sel_hi:[1,0]
	v_pk_mul_f32 v[14:15], v[18:19], v[12:13] op_sel_hi:[1,0]
	s_waitcnt lgkmcnt(2)
	v_pk_mul_f32 v[0:1], v[0:1], v[16:17]
	s_waitcnt lgkmcnt(1)
	v_pk_add_f32 v[4:5], v[4:5], 1.0 op_sel_hi:[1,0]
	v_pk_mul_f32 v[2:3], v[2:3], v[14:15]
	v_pk_add_f32 v[6:7], v[6:7], 1.0 op_sel_hi:[1,0]
	s_waitcnt lgkmcnt(0)
	v_pk_fma_f32 v[0:1], v[4:5], v[0:1], v[8:9]
	v_lshl_add_u64 v[14:15], v[34:35], 0, s[34:35]
	v_pk_fma_f32 v[2:3], v[6:7], v[2:3], v[10:11]
	v_cvt_pk_bf16_f32 v0, v0, v1
	v_pk_mul_f32 v[18:19], v[20:21], v[12:13] op_sel_hi:[1,0]
	v_cvt_pk_bf16_f32 v1, v2, v3
	global_store_dwordx2 v[14:15], v[0:1], off
	ds_read_b128 v[0:3], v80 offset:5120
	ds_read_b128 v[4:7], v94 offset:29696
	ds_read_b128 v[8:11], v94 offset:50176
	v_pk_mul_f32 v[16:17], v[22:23], v[12:13] op_sel_hi:[1,0]
	s_waitcnt lgkmcnt(2)
	v_pk_mul_f32 v[0:1], v[0:1], v[18:19]
	s_waitcnt lgkmcnt(1)
	v_pk_add_f32 v[4:5], v[4:5], 1.0 op_sel_hi:[1,0]
	v_pk_mul_f32 v[2:3], v[2:3], v[16:17]
	v_pk_add_f32 v[6:7], v[6:7], 1.0 op_sel_hi:[1,0]
	s_waitcnt lgkmcnt(0)
	v_pk_fma_f32 v[0:1], v[4:5], v[0:1], v[8:9]
	v_pk_fma_f32 v[2:3], v[6:7], v[2:3], v[10:11]
	v_cvt_pk_bf16_f32 v0, v0, v1
	v_pk_mul_f32 v[18:19], v[24:25], v[12:13] op_sel_hi:[1,0]
	v_cvt_pk_bf16_f32 v1, v2, v3
	global_store_dwordx2 v[14:15], v[0:1], off offset:512
	ds_read_b128 v[0:3], v80 offset:6144
	ds_read_b128 v[4:7], v94 offset:30720
	ds_read_b128 v[8:11], v94 offset:51200
	v_pk_mul_f32 v[16:17], v[26:27], v[12:13] op_sel_hi:[1,0]
	s_waitcnt lgkmcnt(2)
	v_pk_mul_f32 v[0:1], v[18:19], v[0:1]
	s_waitcnt lgkmcnt(1)
	v_pk_add_f32 v[4:5], v[4:5], 1.0 op_sel_hi:[1,0]
	v_pk_mul_f32 v[2:3], v[16:17], v[2:3]
	v_pk_add_f32 v[6:7], v[6:7], 1.0 op_sel_hi:[1,0]
	s_waitcnt lgkmcnt(0)
	v_pk_fma_f32 v[0:1], v[0:1], v[4:5], v[8:9]
	v_pk_fma_f32 v[2:3], v[2:3], v[6:7], v[10:11]
	v_cvt_pk_bf16_f32 v0, v0, v1
	v_pk_mul_f32 v[16:17], v[30:31], v[12:13] op_sel_hi:[1,0]
	v_cvt_pk_bf16_f32 v1, v2, v3
	global_store_dwordx2 v[14:15], v[0:1], off offset:1024
	ds_read_b128 v[0:3], v80 offset:7168
	ds_read_b128 v[4:7], v94 offset:31744
	ds_read_b128 v[8:11], v94 offset:52224
	v_pk_mul_f32 v[12:13], v[28:29], v[12:13] op_sel_hi:[1,0]
	s_waitcnt lgkmcnt(2)
	v_pk_mul_f32 v[2:3], v[16:17], v[2:3]
	v_pk_mul_f32 v[0:1], v[12:13], v[0:1]
	s_waitcnt lgkmcnt(1)
	v_pk_add_f32 v[4:5], v[4:5], 1.0 op_sel_hi:[1,0]
	v_pk_add_f32 v[6:7], v[6:7], 1.0 op_sel_hi:[1,0]
	s_waitcnt lgkmcnt(0)
	v_pk_fma_f32 v[0:1], v[0:1], v[4:5], v[8:9]
	v_pk_fma_f32 v[2:3], v[2:3], v[6:7], v[10:11]
	v_cvt_pk_bf16_f32 v0, v0, v1
	s_nop 0
	v_cvt_pk_bf16_f32 v1, v2, v3
	global_store_dwordx2 v[14:15], v[0:1], off offset:1536
	s_branch .LBB0_340
